# SWA tiles rewritten by hand: K/V fragments shared by the 4 query heads, distance mask folded into accumulator init, unmasked path for interior tiles
# speedup vs baseline: 1.0145x; 1.0087x over previous
; #define LAS __attribute__((address_space(3)))
; __device__ __forceinline__ void drain_wait() { asm volatile("s_waitcnt vmcnt(0)" ::: "memory"); __syncthreads(); }
; __device__ __forceinline__ void swa_phase(LAS unsigned char* lds, const bf16_t* Q, const bf16_t* K, const bf16_t* V, bf16_t* Ob, const float* sink, float negb) {
;     ...
;         const int item = item_of(it, SW_ITEMS, SW_ITEMS); if (item < 0) break;
;         const int b = item >> 8, kvh = (item >> 6) & 3, tb = item & 63;
;         const size_t ctx0 = (size_t)(MLAT + b * NCTX), lat0 = (size_t)(b * SEQ);
;         const int i_lo = tb == 0 ? 2 : 0, i_hi = tb == 63 ? 4 : 6;
;         const int NT = 4 + (i_hi - i_lo);
;         const DmaLane dl = dma_lane(256, kvh * 64, w, lane);
;     ...
;         dma_tile<1>(lds, K, V, SW_ROW0(0), 256, dl, w);
;         dma_tile<1>(lds + SW_BUF, K, V, SW_ROW0(1), 256, dl, w);
;         dma_tile<1>(lds + 2 * SW_BUF, K, V, SW_ROW0(2), 256, dl, w);
;         const int tq = 128 * tb + 16 * w;
;         const size_t qrow = (size_t)(b * SEQ + tq + l15);
;         bf16x8 qf[4][2];
; #pragma unroll
;         for (int grp = 0; grp < 4; ++grp)
; #pragma unroll
;             for (int ds = 0; ds < 2; ++ds) qf[grp][ds] = *(const bf16x8*)(Q + qrow * DM + (4 * kvh + grp) * 64 + 32 * ds + 8 * g);
;         f32x4 O[4][4]; float ls[4];
; #pragma unroll
;         for (int grp = 0; grp < 4; ++grp) { ls[grp] = 0.f;
; #pragma unroll
;             for (int db = 0; db < 4; ++db) O[grp][db] = (f32x4){0.f, 0.f, 0.f, 0.f}; }
;         drain_wait();
;         for (int t = 0; t < 4; ++t) {
;             dma_tile<1>(lds + ((t + 3) & 3) * SW_BUF, K, V, SW_ROW0(t + 3), 256, dl, w);
;             const LAS unsigned char* buf = lds + (t & 3) * SW_BUF;
.LBB0_350:
	s_cmp_lt_i32 s6, 0
	s_cbranch_scc1 .LBB0_357
	s_and_b32 s0, s6, 0x7fffff00
	s_add_i32 s82, s0, 0x8000
	s_lshl_b32 s0, s6, 5
	s_bfe_u32 s42, s6, 0x20006
	s_and_b32 s12, s6, 63
	s_and_b32 s43, s0, 0x7fffe000
	s_cmp_eq_u32 s12, 0
	s_cselect_b32 s7, 2, 0
	s_cmp_eq_u32 s12, 63
	s_cselect_b32 s0, 4, 6
	s_sub_i32 s44, s0, s7
	s_lshl_b64 s[8:9], s[82:83], 9
	s_add_u32 s0, s67, s8
	s_addc_u32 s1, s4, s9
	v_lshl_or_b32 v4, s42, 7, v188
	s_add_u32 s10, s5, s8
	v_or_b32_e32 v212, v4, v189
	s_addc_u32 s11, s58, s9
	s_add_i32 s6, s40, 0x2000
	s_mov_b32 s13, m0
	s_mov_b32 m0, s40
	s_nop 0
	global_load_lds_dwordx4 v212, s[0:1]
	s_mov_b32 m0, s13
	v_or_b32_e32 v213, v4, v190
	s_mov_b32 s0, m0
	s_mov_b32 m0, s6
	s_nop 0
	global_load_lds_dwordx4 v213, s[10:11]
	s_mov_b32 m0, s0
	s_or_b32 s6, s8, 0x8000
	s_add_u32 s0, s67, s6
	s_addc_u32 s1, s4, s9
	s_add_u32 s10, s5, s6
	s_addc_u32 s11, s58, s9
	s_add_i32 s6, s40, 0x4000
	s_mov_b32 s14, m0
	s_mov_b32 m0, s6
	s_nop 0
	global_load_lds_dwordx4 v212, s[0:1]
	s_mov_b32 m0, s14
	s_add_i32 s13, s40, 0x6000
	s_mov_b32 s0, m0
	s_mov_b32 m0, s13
	s_nop 0
	global_load_lds_dwordx4 v213, s[10:11]
	s_mov_b32 m0, s0
	s_or_b32 s6, s8, 0x10000
	s_add_u32 s0, s67, s6
	s_addc_u32 s1, s4, s9
	s_add_u32 s10, s5, s6
	s_addc_u32 s11, s58, s9
	s_add_i32 s6, s40, 0x8000
	s_mov_b32 s14, m0
	s_mov_b32 m0, s6
	s_nop 0
	global_load_lds_dwordx4 v212, s[0:1]
	s_mov_b32 m0, s14
	s_add_i32 s13, s40, 0xa000
	s_mov_b32 s0, m0
	s_mov_b32 m0, s13
	s_nop 0
	global_load_lds_dwordx4 v213, s[10:11]
	s_mov_b32 m0, s0
	s_lshl_b32 s45, s12, 7
	s_add_i32 s0, s45, s39
	s_add_i32 s1, s0, s43
	v_or_b32_e32 v4, s1, v187
	v_ashrrev_i32_e32 v5, 31, v4
	v_lshlrev_b64 v[126:127], 11, v[4:5]
	v_lshl_add_u64 v[4:5], v[122:123], 0, v[126:127]
	s_lshl_b32 s36, s42, 9
	s_mov_b32 s37, s83
	v_lshl_add_u64 v[32:33], v[4:5], 0, s[36:37]
	global_load_dwordx4 v[4:7], v[32:33], off
	global_load_dwordx4 v[8:11], v[32:33], off offset:128
	global_load_dwordx4 v[12:15], v[32:33], off offset:64
	global_load_dwordx4 v[16:19], v[32:33], off offset:192
	global_load_dwordx4 v[20:23], v[32:33], off offset:256
	global_load_dwordx4 v[24:27], v[32:33], off offset:320
	global_load_dwordx4 v[28:31], v[32:33], off offset:384
	s_nop 0
	global_load_dwordx4 v[32:35], v[32:33], off offset:448
	s_lshl_b32 s37, s42, 8
	s_add_i32 s46, s44, 4
	s_or_b32 s1, s8, 0x18000
	s_add_u32 s10, s67, s1
	s_addc_u32 s11, s4, s9
	s_add_u32 s8, s5, s1
	s_addc_u32 s9, s58, s9
	s_add_i32 s1, s40, 0xc000
	s_waitcnt vmcnt(0)
	s_barrier
	s_mov_b32 s12, m0
	s_mov_b32 m0, s1
	s_nop 0
	global_load_lds_dwordx4 v212, s[10:11]
	s_mov_b32 m0, s12
	v_add_u32_e32 v91, v154, v192
	s_add_i32 s6, s40, 0xe000
	s_mov_b32 s1, m0
	s_mov_b32 m0, s6
	s_nop 0
	global_load_lds_dwordx4 v213, s[8:9]
	s_mov_b32 m0, s1
	v_mov_b32_e32 v64, 0
	v_mov_b32_e32 v65, 0
	v_mov_b32_e32 v66, 0
	v_mov_b32_e32 v67, 0
	v_mov_b32_e32 v60, 0
	v_mov_b32_e32 v61, 0
	v_mov_b32_e32 v62, 0
	v_mov_b32_e32 v63, 0
	v_mov_b32_e32 v56, 0
	v_mov_b32_e32 v57, 0
	v_mov_b32_e32 v58, 0
	v_mov_b32_e32 v59, 0
	v_mov_b32_e32 v52, 0
	v_mov_b32_e32 v53, 0
	v_mov_b32_e32 v54, 0
	v_mov_b32_e32 v55, 0
	v_mov_b32_e32 v131, 0
	v_mov_b32_e32 v48, 0
	v_mov_b32_e32 v49, 0
	v_mov_b32_e32 v50, 0
	v_mov_b32_e32 v51, 0
	v_mov_b32_e32 v44, 0
	v_mov_b32_e32 v45, 0
	v_mov_b32_e32 v46, 0
	v_mov_b32_e32 v47, 0
	v_mov_b32_e32 v40, 0
	v_mov_b32_e32 v41, 0
	v_mov_b32_e32 v42, 0
	v_mov_b32_e32 v43, 0
	v_mov_b32_e32 v36, 0
	v_mov_b32_e32 v37, 0
	v_mov_b32_e32 v38, 0
	v_mov_b32_e32 v39, 0
	v_mov_b32_e32 v130, 0
	v_mov_b32_e32 v72, 0
	v_mov_b32_e32 v73, 0
	v_mov_b32_e32 v74, 0
	v_mov_b32_e32 v75, 0
	v_mov_b32_e32 v84, 0
	v_mov_b32_e32 v85, 0
	v_mov_b32_e32 v86, 0
	v_mov_b32_e32 v87, 0
	v_mov_b32_e32 v88, 0
	v_mov_b32_e32 v89, 0
	v_mov_b32_e32 v90, 0
	v_mov_b32_e32 v91, 0
	v_mov_b32_e32 v96, 0
	v_mov_b32_e32 v97, 0
	v_mov_b32_e32 v98, 0
	v_mov_b32_e32 v99, 0
	v_mov_b32_e32 v129, 0
	v_mov_b32_e32 v68, 0
	v_mov_b32_e32 v69, 0
	v_mov_b32_e32 v70, 0
	v_mov_b32_e32 v71, 0
	v_mov_b32_e32 v76, 0
	v_mov_b32_e32 v77, 0
	v_mov_b32_e32 v78, 0
	v_mov_b32_e32 v79, 0
	v_mov_b32_e32 v80, 0
	v_mov_b32_e32 v81, 0
	v_mov_b32_e32 v82, 0
	v_mov_b32_e32 v83, 0
	v_mov_b32_e32 v92, 0
	v_mov_b32_e32 v93, 0
	v_mov_b32_e32 v94, 0
	v_mov_b32_e32 v95, 0
	v_mov_b32_e32 v128, 0
	s_lshl_b32 s47, s7, 6
	s_add_i32 s7, s45, s47
	s_addk_i32 s7, 0xff80
	s_ashr_i32 s8, s7, 31
	s_add_u32 s7, s43, s7
	s_addc_u32 s8, 0, s8
	s_mov_b32 s1, 0
	s_mov_b32 s6, 4
	s_mov_b32 s34, 0
	v_add_u32_e32 v100, s34, v191
	v_add3_u32 v135, s34, v203, v198
	v_add_u32_e32 v102, v100, v193
	v_add_u32_e32 v100, v100, v192
	ds_read_b128 v[160:163], v100
	ds_read_b128 v[164:167], v102
	ds_read_b128 v[168:171], v100 offset:2048
	ds_read_b128 v[172:175], v102 offset:2048
	v_add_u32_e32 v103, v135, v199
	v_add_u32_e32 v133, v135, v200
	v_add_u32_e32 v134, v135, v201
	v_add_u32_e32 v135, v135, v202
	s_waitcnt lgkmcnt(0)
; #define LAS __attribute__((address_space(3)))
; __device__ __forceinline__ s16x4 vtr(const LAS unsigned char* p) { return __builtin_bit_cast(s16x4, __builtin_amdgcn_ds_read_tr16_b64_v4i16((LAS v4i16_t*)p)); }
;     ...
; #pragma unroll
;     for (int gh = 0; gh < 4 / GPB; ++gh) {
;         f32x4 S[GPB][4];
; #pragma unroll
;         for (int kb = 0; kb < 4; ++kb) {
;             const bf16x8 kf0 = *(const LAS bf16x8*)(kb0 + (16 * kb) * 128 + kx0), kf1 = *(const LAS bf16x8*)(kb0 + (16 * kb) * 128 + kx1);
; #pragma unroll
;             for (int gi = 0; gi < GPB; ++gi) { S[gi][kb] = __builtin_amdgcn_mfma_f32_16x16x32_bf16(kf0, qf[GPB * gh + gi][0], cinit, 0, 0, 0);
;                 S[gi][kb] = __builtin_amdgcn_mfma_f32_16x16x32_bf16(kf1, qf[GPB * gh + gi][1], S[gi][kb], 0, 0, 0); } }
;         bf16x8 pf[GPB][2];
; #pragma unroll
;         for (int gi = 0; gi < GPB; ++gi) {
;             if (MASK) {
; #pragma unroll
;                 for (int kb = 0; kb < 4; ++kb)
; #pragma unroll
;                     for (int i = 0; i < 4; ++i) { const int rel = rel0 + 16 * kb + 4 * g + i; S[gi][kb][i] = ((unsigned)(rel + 128) > 256u) ? NEGBIG : S[gi][kb][i]; }
;             }
;             ls[GPB * gh + gi] += exp_step<4>(S[gi]);
;             pf[gi][0] = pack8(S[gi][0], S[gi][1]); pf[gi][1] = pack8(S[gi][2], S[gi][3]);
;         }
; #pragma unroll
;         for (int kc = 0; kc < 2; ++kc)
; #pragma unroll
;             for (int db = 0; db < 4; ++db) {
;                 const LAS unsigned char* va = vrow + ((db ^ swz) << 5) + (32 * kc) * 128;
;                 const bf16x8 vf = cat8(vtr(va), vtr(va + 16 * 128));
; #pragma unroll
;                 for (int gi = 0; gi < GPB; ++gi) O[GPB * gh + gi][db] = __builtin_amdgcn_mfma_f32_16x16x32_bf16(vf, pf[gi][kc], O[GPB * gh + gi][db], 0, 0, 0);
;             }
; __device__ __forceinline__ void swa_phase(LAS unsigned char* lds, const bf16_t* Q, const bf16_t* K, const bf16_t* V, bf16_t* Ob, const float* sink, float negb) {
;     ...
;         for (int t = 0; t < 4; ++t) {
;             dma_tile<1>(lds + ((t + 3) & 3) * SW_BUF, K, V, SW_ROW0(t + 3), 256, dl, w);
;             const LAS unsigned char* buf = lds + (t & 3) * SW_BUF;
;             full_tile<0, 2, 2>(O, ls, qf, negb, buf, buf + 8192, lane, 0);
;             ring_wait<2>();
	v_mfma_f32_16x16x32_bf16 v[104:107], v[160:163], v[4:7], v[0:3]
	v_mfma_f32_16x16x32_bf16 v[108:111], v[168:171], v[4:7], v[0:3]
	v_mfma_f32_16x16x32_bf16 v[112:115], v[160:163], v[8:11], v[0:3]
	v_mfma_f32_16x16x32_bf16 v[116:119], v[168:171], v[8:11], v[0:3]
	v_mfma_f32_16x16x32_bf16 v[136:139], v[160:163], v[20:23], v[0:3]
	v_mfma_f32_16x16x32_bf16 v[140:143], v[168:171], v[20:23], v[0:3]
	v_mfma_f32_16x16x32_bf16 v[176:179], v[160:163], v[28:31], v[0:3]
	v_mfma_f32_16x16x32_bf16 v[232:235], v[168:171], v[28:31], v[0:3]
	v_mfma_f32_16x16x32_bf16 v[104:107], v[164:167], v[12:15], v[104:107]
	v_mfma_f32_16x16x32_bf16 v[108:111], v[172:175], v[12:15], v[108:111]
	v_mfma_f32_16x16x32_bf16 v[112:115], v[164:167], v[16:19], v[112:115]
	v_mfma_f32_16x16x32_bf16 v[116:119], v[172:175], v[16:19], v[116:119]
	v_mfma_f32_16x16x32_bf16 v[136:139], v[164:167], v[24:27], v[136:139]
	v_mfma_f32_16x16x32_bf16 v[140:143], v[172:175], v[24:27], v[140:143]
	v_mfma_f32_16x16x32_bf16 v[176:179], v[164:167], v[32:35], v[176:179]
	v_mfma_f32_16x16x32_bf16 v[232:235], v[172:175], v[32:35], v[232:235]
	ds_read_b64_tr_b16 v[216:217], v103 offset:8192
	ds_read_b64_tr_b16 v[218:219], v103 offset:10240
	ds_read_b64_tr_b16 v[220:221], v133 offset:8192
	ds_read_b64_tr_b16 v[222:223], v133 offset:10240
	ds_read_b64_tr_b16 v[224:225], v134 offset:8192
	ds_read_b64_tr_b16 v[226:227], v134 offset:10240
	ds_read_b64_tr_b16 v[228:229], v135 offset:8192
	ds_read_b64_tr_b16 v[230:231], v135 offset:10240
	ds_read_b128 v[160:163], v100 offset:4096
	ds_read_b128 v[164:167], v102 offset:4096
	ds_read_b128 v[168:171], v100 offset:6144
	ds_read_b128 v[172:175], v102 offset:6144
	v_exp_f32_e32 v104, v104
	v_exp_f32_e32 v105, v105
	v_exp_f32_e32 v106, v106
	v_add_f32_e32 v144, v104, v105
	v_exp_f32_e32 v107, v107
	v_exp_f32_e32 v108, v108
	v_add_f32_e32 v144, v144, v106
	v_exp_f32_e32 v109, v109
	v_add_f32_e32 v144, v144, v107
	v_exp_f32_e32 v110, v110
	v_add_f32_e32 v144, v144, v108
	v_exp_f32_e32 v111, v111
	v_add_f32_e32 v144, v144, v109
	v_cvt_pk_bf16_f32 v104, v104, v105
	v_add_f32_e32 v144, v144, v110
	v_cvt_pk_bf16_f32 v105, v106, v107
	v_cvt_pk_bf16_f32 v106, v108, v109
	v_cvt_pk_bf16_f32 v107, v110, v111
	v_add_f32_e32 v144, v144, v111
	v_add_f32_e32 v131, v131, v144
	v_exp_f32_e32 v112, v112
	v_exp_f32_e32 v113, v113
	v_exp_f32_e32 v114, v114
	v_add_f32_e32 v144, v112, v113
	v_exp_f32_e32 v115, v115
	v_exp_f32_e32 v116, v116
	v_add_f32_e32 v144, v144, v114
	v_exp_f32_e32 v117, v117
	v_add_f32_e32 v144, v144, v115
	v_exp_f32_e32 v118, v118
	v_add_f32_e32 v144, v144, v116
	v_exp_f32_e32 v119, v119
	v_add_f32_e32 v144, v144, v117
	v_cvt_pk_bf16_f32 v112, v112, v113
	v_add_f32_e32 v144, v144, v118
	v_cvt_pk_bf16_f32 v113, v114, v115
	v_cvt_pk_bf16_f32 v114, v116, v117
	v_cvt_pk_bf16_f32 v115, v118, v119
	v_add_f32_e32 v144, v144, v119
	v_add_f32_e32 v130, v130, v144
	v_exp_f32_e32 v136, v136
	v_exp_f32_e32 v137, v137
	v_exp_f32_e32 v138, v138
	v_add_f32_e32 v144, v136, v137
	v_exp_f32_e32 v139, v139
	v_exp_f32_e32 v140, v140
	v_add_f32_e32 v144, v144, v138
	v_exp_f32_e32 v141, v141
	v_add_f32_e32 v144, v144, v139
	v_exp_f32_e32 v142, v142
	v_add_f32_e32 v144, v144, v140
	v_exp_f32_e32 v143, v143
	v_add_f32_e32 v144, v144, v141
	v_cvt_pk_bf16_f32 v136, v136, v137
	v_add_f32_e32 v144, v144, v142
	v_cvt_pk_bf16_f32 v137, v138, v139
	v_cvt_pk_bf16_f32 v138, v140, v141
	v_cvt_pk_bf16_f32 v139, v142, v143
	v_add_f32_e32 v144, v144, v143
	v_add_f32_e32 v129, v129, v144
	v_exp_f32_e32 v176, v176
	v_exp_f32_e32 v177, v177
	v_exp_f32_e32 v178, v178
	v_add_f32_e32 v144, v176, v177
	v_exp_f32_e32 v179, v179
	v_exp_f32_e32 v232, v232
	v_add_f32_e32 v144, v144, v178
	v_exp_f32_e32 v233, v233
	v_add_f32_e32 v144, v144, v179
	v_exp_f32_e32 v234, v234
	v_add_f32_e32 v144, v144, v232
	v_exp_f32_e32 v235, v235
	v_add_f32_e32 v144, v144, v233
	v_cvt_pk_bf16_f32 v176, v176, v177
	v_add_f32_e32 v144, v144, v234
	v_cvt_pk_bf16_f32 v177, v178, v179
	v_cvt_pk_bf16_f32 v178, v232, v233
	v_cvt_pk_bf16_f32 v179, v234, v235
	v_add_f32_e32 v144, v144, v235
	v_add_f32_e32 v128, v128, v144
	s_waitcnt lgkmcnt(4)
	v_mfma_f32_16x16x32_bf16 v[64:67], v[216:219], v[104:107], v[64:67]
	v_mfma_f32_16x16x32_bf16 v[60:63], v[220:223], v[104:107], v[60:63]
	v_mfma_f32_16x16x32_bf16 v[56:59], v[224:227], v[104:107], v[56:59]
	v_mfma_f32_16x16x32_bf16 v[52:55], v[228:231], v[104:107], v[52:55]
	v_mfma_f32_16x16x32_bf16 v[48:51], v[216:219], v[112:115], v[48:51]
	v_mfma_f32_16x16x32_bf16 v[44:47], v[220:223], v[112:115], v[44:47]
	v_mfma_f32_16x16x32_bf16 v[40:43], v[224:227], v[112:115], v[40:43]
	v_mfma_f32_16x16x32_bf16 v[36:39], v[228:231], v[112:115], v[36:39]
	v_mfma_f32_16x16x32_bf16 v[72:75], v[216:219], v[136:139], v[72:75]
	v_mfma_f32_16x16x32_bf16 v[84:87], v[220:223], v[136:139], v[84:87]
	v_mfma_f32_16x16x32_bf16 v[88:91], v[224:227], v[136:139], v[88:91]
	v_mfma_f32_16x16x32_bf16 v[96:99], v[228:231], v[136:139], v[96:99]
	v_mfma_f32_16x16x32_bf16 v[68:71], v[216:219], v[176:179], v[68:71]
	v_mfma_f32_16x16x32_bf16 v[76:79], v[220:223], v[176:179], v[76:79]
	v_mfma_f32_16x16x32_bf16 v[80:83], v[224:227], v[176:179], v[80:83]
	v_mfma_f32_16x16x32_bf16 v[92:95], v[228:231], v[176:179], v[92:95]
	s_waitcnt lgkmcnt(0)
; #define LAS __attribute__((address_space(3)))
; __device__ __forceinline__ s16x4 vtr(const LAS unsigned char* p) { return __builtin_bit_cast(s16x4, __builtin_amdgcn_ds_read_tr16_b64_v4i16((LAS v4i16_t*)p)); }
;     ...
; #pragma unroll
;     for (int gh = 0; gh < 4 / GPB; ++gh) {
;         f32x4 S[GPB][4];
; #pragma unroll
;         for (int kb = 0; kb < 4; ++kb) {
;             const bf16x8 kf0 = *(const LAS bf16x8*)(kb0 + (16 * kb) * 128 + kx0), kf1 = *(const LAS bf16x8*)(kb0 + (16 * kb) * 128 + kx1);
; #pragma unroll
;             for (int gi = 0; gi < GPB; ++gi) { S[gi][kb] = __builtin_amdgcn_mfma_f32_16x16x32_bf16(kf0, qf[GPB * gh + gi][0], cinit, 0, 0, 0);
;                 S[gi][kb] = __builtin_amdgcn_mfma_f32_16x16x32_bf16(kf1, qf[GPB * gh + gi][1], S[gi][kb], 0, 0, 0); } }
;         bf16x8 pf[GPB][2];
; #pragma unroll
;         for (int gi = 0; gi < GPB; ++gi) {
;             if (MASK) {
; #pragma unroll
;                 for (int kb = 0; kb < 4; ++kb)
; #pragma unroll
;                     for (int i = 0; i < 4; ++i) { const int rel = rel0 + 16 * kb + 4 * g + i; S[gi][kb][i] = ((unsigned)(rel + 128) > 256u) ? NEGBIG : S[gi][kb][i]; }
;             }
;             ls[GPB * gh + gi] += exp_step<4>(S[gi]);
;             pf[gi][0] = pack8(S[gi][0], S[gi][1]); pf[gi][1] = pack8(S[gi][2], S[gi][3]);
;         }
; #pragma unroll
;         for (int kc = 0; kc < 2; ++kc)
; #pragma unroll
;             for (int db = 0; db < 4; ++db) {
;                 const LAS unsigned char* va = vrow + ((db ^ swz) << 5) + (32 * kc) * 128;
;                 const bf16x8 vf = cat8(vtr(va), vtr(va + 16 * 128));
; #pragma unroll
;                 for (int gi = 0; gi < GPB; ++gi) O[GPB * gh + gi][db] = __builtin_amdgcn_mfma_f32_16x16x32_bf16(vf, pf[gi][kc], O[GPB * gh + gi][db], 0, 0, 0);
;             }
; __device__ __forceinline__ void swa_phase(LAS unsigned char* lds, const bf16_t* Q, const bf16_t* K, const bf16_t* V, bf16_t* Ob, const float* sink, float negb) {
;     ...
;         for (int t = 0; t < 4; ++t) {
;             dma_tile<1>(lds + ((t + 3) & 3) * SW_BUF, K, V, SW_ROW0(t + 3), 256, dl, w);
;             const LAS unsigned char* buf = lds + (t & 3) * SW_BUF;
;             full_tile<0, 2, 2>(O, ls, qf, negb, buf, buf + 8192, lane, 0);
;             ring_wait<2>();
	v_mfma_f32_16x16x32_bf16 v[104:107], v[160:163], v[4:7], v[0:3]
	v_mfma_f32_16x16x32_bf16 v[108:111], v[168:171], v[4:7], v[0:3]
	v_mfma_f32_16x16x32_bf16 v[112:115], v[160:163], v[8:11], v[0:3]
	v_mfma_f32_16x16x32_bf16 v[116:119], v[168:171], v[8:11], v[0:3]
	v_mfma_f32_16x16x32_bf16 v[136:139], v[160:163], v[20:23], v[0:3]
	v_mfma_f32_16x16x32_bf16 v[140:143], v[168:171], v[20:23], v[0:3]
	v_mfma_f32_16x16x32_bf16 v[176:179], v[160:163], v[28:31], v[0:3]
	v_mfma_f32_16x16x32_bf16 v[232:235], v[168:171], v[28:31], v[0:3]
	v_mfma_f32_16x16x32_bf16 v[104:107], v[164:167], v[12:15], v[104:107]
	v_mfma_f32_16x16x32_bf16 v[108:111], v[172:175], v[12:15], v[108:111]
	v_mfma_f32_16x16x32_bf16 v[112:115], v[164:167], v[16:19], v[112:115]
	v_mfma_f32_16x16x32_bf16 v[116:119], v[172:175], v[16:19], v[116:119]
	v_mfma_f32_16x16x32_bf16 v[136:139], v[164:167], v[24:27], v[136:139]
	v_mfma_f32_16x16x32_bf16 v[140:143], v[172:175], v[24:27], v[140:143]
	v_mfma_f32_16x16x32_bf16 v[176:179], v[164:167], v[32:35], v[176:179]
	v_mfma_f32_16x16x32_bf16 v[232:235], v[172:175], v[32:35], v[232:235]
	ds_read_b64_tr_b16 v[216:217], v103 offset:12288
	ds_read_b64_tr_b16 v[218:219], v103 offset:14336
	ds_read_b64_tr_b16 v[220:221], v133 offset:12288
	ds_read_b64_tr_b16 v[222:223], v133 offset:14336
	ds_read_b64_tr_b16 v[224:225], v134 offset:12288
	ds_read_b64_tr_b16 v[226:227], v134 offset:14336
	ds_read_b64_tr_b16 v[228:229], v135 offset:12288
	ds_read_b64_tr_b16 v[230:231], v135 offset:14336
	v_exp_f32_e32 v104, v104
	v_exp_f32_e32 v105, v105
	v_exp_f32_e32 v106, v106
	v_add_f32_e32 v144, v104, v105
	v_exp_f32_e32 v107, v107
	v_exp_f32_e32 v108, v108
	v_add_f32_e32 v144, v144, v106
	v_exp_f32_e32 v109, v109
	v_add_f32_e32 v144, v144, v107
	v_exp_f32_e32 v110, v110
	v_add_f32_e32 v144, v144, v108
	v_exp_f32_e32 v111, v111
	v_add_f32_e32 v144, v144, v109
	v_cvt_pk_bf16_f32 v104, v104, v105
	v_add_f32_e32 v144, v144, v110
	v_cvt_pk_bf16_f32 v105, v106, v107
	v_cvt_pk_bf16_f32 v106, v108, v109
	v_cvt_pk_bf16_f32 v107, v110, v111
	v_add_f32_e32 v144, v144, v111
	v_add_f32_e32 v131, v131, v144
	v_exp_f32_e32 v112, v112
	v_exp_f32_e32 v113, v113
	v_exp_f32_e32 v114, v114
	v_add_f32_e32 v144, v112, v113
	v_exp_f32_e32 v115, v115
	v_exp_f32_e32 v116, v116
	v_add_f32_e32 v144, v144, v114
	v_exp_f32_e32 v117, v117
	v_add_f32_e32 v144, v144, v115
	v_exp_f32_e32 v118, v118
	v_add_f32_e32 v144, v144, v116
	v_exp_f32_e32 v119, v119
	v_add_f32_e32 v144, v144, v117
	v_cvt_pk_bf16_f32 v112, v112, v113
	v_add_f32_e32 v144, v144, v118
	v_cvt_pk_bf16_f32 v113, v114, v115
	v_cvt_pk_bf16_f32 v114, v116, v117
	v_cvt_pk_bf16_f32 v115, v118, v119
	v_add_f32_e32 v144, v144, v119
	v_add_f32_e32 v130, v130, v144
	v_exp_f32_e32 v136, v136
	v_exp_f32_e32 v137, v137
	v_exp_f32_e32 v138, v138
	v_add_f32_e32 v144, v136, v137
	v_exp_f32_e32 v139, v139
	v_exp_f32_e32 v140, v140
	v_add_f32_e32 v144, v144, v138
	v_exp_f32_e32 v141, v141
	v_add_f32_e32 v144, v144, v139
	v_exp_f32_e32 v142, v142
	v_add_f32_e32 v144, v144, v140
	v_exp_f32_e32 v143, v143
	v_add_f32_e32 v144, v144, v141
	v_cvt_pk_bf16_f32 v136, v136, v137
	v_add_f32_e32 v144, v144, v142
	v_cvt_pk_bf16_f32 v137, v138, v139
	v_cvt_pk_bf16_f32 v138, v140, v141
	v_cvt_pk_bf16_f32 v139, v142, v143
	v_add_f32_e32 v144, v144, v143
	v_add_f32_e32 v129, v129, v144
	v_exp_f32_e32 v176, v176
	v_exp_f32_e32 v177, v177
	v_exp_f32_e32 v178, v178
	v_add_f32_e32 v144, v176, v177
	v_exp_f32_e32 v179, v179
	v_exp_f32_e32 v232, v232
	v_add_f32_e32 v144, v144, v178
	v_exp_f32_e32 v233, v233
	v_add_f32_e32 v144, v144, v179
	v_exp_f32_e32 v234, v234
	v_add_f32_e32 v144, v144, v232
	v_exp_f32_e32 v235, v235
	v_add_f32_e32 v144, v144, v233
	v_cvt_pk_bf16_f32 v176, v176, v177
	v_add_f32_e32 v144, v144, v234
	v_cvt_pk_bf16_f32 v177, v178, v179
	v_cvt_pk_bf16_f32 v178, v232, v233
	v_cvt_pk_bf16_f32 v179, v234, v235
	v_add_f32_e32 v144, v144, v235
	v_add_f32_e32 v128, v128, v144
	s_waitcnt lgkmcnt(0)
	v_mfma_f32_16x16x32_bf16 v[64:67], v[216:219], v[104:107], v[64:67]
	v_mfma_f32_16x16x32_bf16 v[60:63], v[220:223], v[104:107], v[60:63]
	v_mfma_f32_16x16x32_bf16 v[56:59], v[224:227], v[104:107], v[56:59]
	v_mfma_f32_16x16x32_bf16 v[52:55], v[228:231], v[104:107], v[52:55]
	v_mfma_f32_16x16x32_bf16 v[48:51], v[216:219], v[112:115], v[48:51]
	v_mfma_f32_16x16x32_bf16 v[44:47], v[220:223], v[112:115], v[44:47]
	v_mfma_f32_16x16x32_bf16 v[40:43], v[224:227], v[112:115], v[40:43]
	v_mfma_f32_16x16x32_bf16 v[36:39], v[228:231], v[112:115], v[36:39]
	v_mfma_f32_16x16x32_bf16 v[72:75], v[216:219], v[136:139], v[72:75]
	v_mfma_f32_16x16x32_bf16 v[84:87], v[220:223], v[136:139], v[84:87]
	v_mfma_f32_16x16x32_bf16 v[88:91], v[224:227], v[136:139], v[88:91]
	v_mfma_f32_16x16x32_bf16 v[96:99], v[228:231], v[136:139], v[96:99]
	v_mfma_f32_16x16x32_bf16 v[68:71], v[216:219], v[176:179], v[68:71]
	v_mfma_f32_16x16x32_bf16 v[76:79], v[220:223], v[176:179], v[76:79]
	v_mfma_f32_16x16x32_bf16 v[80:83], v[224:227], v[176:179], v[80:83]
	v_mfma_f32_16x16x32_bf16 v[92:95], v[228:231], v[176:179], v[92:95]
	s_waitcnt vmcnt(4)
	s_barrier
; #define LAS __attribute__((address_space(3)))
; __device__ __forceinline__ s16x4 vtr(const LAS unsigned char* p) { return __builtin_bit_cast(s16x4, __builtin_amdgcn_ds_read_tr16_b64_v4i16((LAS v4i16_t*)p)); }
; __device__ __forceinline__ bf16x8 cat8(s16x4 a, s16x4 b) { return (bf16x8){a[0], a[1], a[2], a[3], b[0], b[1], b[2], b[3]}; }
;     ...
; #pragma unroll
;     for (int gh = 0; gh < 4 / GPB; ++gh) {
;         f32x4 S[GPB][4];
; #pragma unroll
;         for (int kb = 0; kb < 4; ++kb) {
;             const bf16x8 kf0 = *(const LAS bf16x8*)(kb0 + (16 * kb) * 128 + kx0), kf1 = *(const LAS bf16x8*)(kb0 + (16 * kb) * 128 + kx1);
; #pragma unroll
;             for (int gi = 0; gi < GPB; ++gi) { S[gi][kb] = __builtin_amdgcn_mfma_f32_16x16x32_bf16(kf0, qf[GPB * gh + gi][0], cinit, 0, 0, 0);
;                 S[gi][kb] = __builtin_amdgcn_mfma_f32_16x16x32_bf16(kf1, qf[GPB * gh + gi][1], S[gi][kb], 0, 0, 0); } }
;         bf16x8 pf[GPB][2];
; #pragma unroll
;         for (int gi = 0; gi < GPB; ++gi) {
;             if (MASK) {
; #pragma unroll
;                 for (int kb = 0; kb < 4; ++kb)
; #pragma unroll
;                     for (int i = 0; i < 4; ++i) { const int rel = rel0 + 16 * kb + 4 * g + i; S[gi][kb][i] = ((unsigned)(rel + 128) > 256u) ? NEGBIG : S[gi][kb][i]; }
;             }
;             ls[GPB * gh + gi] += exp_step<4>(S[gi]);
;             pf[gi][0] = pack8(S[gi][0], S[gi][1]); pf[gi][1] = pack8(S[gi][2], S[gi][3]);
;         }
; #pragma unroll
;         for (int kc = 0; kc < 2; ++kc)
; #pragma unroll
;             for (int db = 0; db < 4; ++db) {
;                 const LAS unsigned char* va = vrow + ((db ^ swz) << 5) + (32 * kc) * 128;
;                 const bf16x8 vf = cat8(vtr(va), vtr(va + 16 * 128));
; #pragma unroll
;                 for (int gi = 0; gi < GPB; ++gi) O[GPB * gh + gi][db] = __builtin_amdgcn_mfma_f32_16x16x32_bf16(vf, pf[gi][kc], O[GPB * gh + gi][db], 0, 0, 0);
;             }
; __device__ __forceinline__ void swa_phase(LAS unsigned char* lds, const bf16_t* Q, const bf16_t* K, const bf16_t* V, bf16_t* Ob, const float* sink, float negb) {
;     ...
;             dma_tile<1>(lds + ((t + 3) & 3) * SW_BUF, K, V, SW_ROW0(t + 3), 256, dl, w);
;             const LAS unsigned char* buf = lds + (t & 3) * SW_BUF;
;             full_tile<0, 2, 2>(O, ls, qf, negb, buf, buf + 8192, lane, 0);
;             ring_wait<2>();
	s_cmp_lt_u32 s6, s46
	s_cselect_b32 s11, s8, 0
	s_cselect_b32 s10, s7, s82
	s_lshl_b64 s[10:11], s[10:11], 9
	s_add_u32 s12, s67, s10
	s_addc_u32 s13, s4, s11
	s_add_u32 s10, s5, s10
	s_addc_u32 s11, s58, s11
	s_add_i32 s9, s40, s1
	s_mov_b32 s15, m0
	s_mov_b32 m0, s9
	s_nop 0
	global_load_lds_dwordx4 v212, s[12:13]
	s_mov_b32 m0, s15
	s_add_i32 s14, s9, 0x2000
	s_mov_b32 s9, m0
	s_mov_b32 m0, s14
	s_nop 0
	global_load_lds_dwordx4 v213, s[10:11]
	s_mov_b32 m0, s9
	s_add_i32 s34, s1, 0x4000
	v_add_u32_e32 v100, s34, v191
	v_add3_u32 v135, s34, v203, v198
	v_add_u32_e32 v102, v100, v193
	v_add_u32_e32 v100, v100, v192
	ds_read_b128 v[160:163], v100
	ds_read_b128 v[164:167], v102
	ds_read_b128 v[168:171], v100 offset:2048
	ds_read_b128 v[172:175], v102 offset:2048
	v_add_u32_e32 v103, v135, v199
	v_add_u32_e32 v133, v135, v200
	v_add_u32_e32 v134, v135, v201
	v_add_u32_e32 v135, v135, v202
	s_waitcnt lgkmcnt(0)
	v_mfma_f32_16x16x32_bf16 v[104:107], v[160:163], v[4:7], v[0:3]
	v_mfma_f32_16x16x32_bf16 v[108:111], v[168:171], v[4:7], v[0:3]
	v_mfma_f32_16x16x32_bf16 v[112:115], v[160:163], v[8:11], v[0:3]
	v_mfma_f32_16x16x32_bf16 v[116:119], v[168:171], v[8:11], v[0:3]
	v_mfma_f32_16x16x32_bf16 v[136:139], v[160:163], v[20:23], v[0:3]
	v_mfma_f32_16x16x32_bf16 v[140:143], v[168:171], v[20:23], v[0:3]
	v_mfma_f32_16x16x32_bf16 v[176:179], v[160:163], v[28:31], v[0:3]
	v_mfma_f32_16x16x32_bf16 v[232:235], v[168:171], v[28:31], v[0:3]
	v_mfma_f32_16x16x32_bf16 v[104:107], v[164:167], v[12:15], v[104:107]
	v_mfma_f32_16x16x32_bf16 v[108:111], v[172:175], v[12:15], v[108:111]
	v_mfma_f32_16x16x32_bf16 v[112:115], v[164:167], v[16:19], v[112:115]
	v_mfma_f32_16x16x32_bf16 v[116:119], v[172:175], v[16:19], v[116:119]
	v_mfma_f32_16x16x32_bf16 v[136:139], v[164:167], v[24:27], v[136:139]
	v_mfma_f32_16x16x32_bf16 v[140:143], v[172:175], v[24:27], v[140:143]
	v_mfma_f32_16x16x32_bf16 v[176:179], v[164:167], v[32:35], v[176:179]
	v_mfma_f32_16x16x32_bf16 v[232:235], v[172:175], v[32:35], v[232:235]
	ds_read_b64_tr_b16 v[216:217], v103 offset:8192
	ds_read_b64_tr_b16 v[218:219], v103 offset:10240
	ds_read_b64_tr_b16 v[220:221], v133 offset:8192
	ds_read_b64_tr_b16 v[222:223], v133 offset:10240
	ds_read_b64_tr_b16 v[224:225], v134 offset:8192
	ds_read_b64_tr_b16 v[226:227], v134 offset:10240
	ds_read_b64_tr_b16 v[228:229], v135 offset:8192
	ds_read_b64_tr_b16 v[230:231], v135 offset:10240
	ds_read_b128 v[160:163], v100 offset:4096
	ds_read_b128 v[164:167], v102 offset:4096
	ds_read_b128 v[168:171], v100 offset:6144
	ds_read_b128 v[172:175], v102 offset:6144
	v_exp_f32_e32 v104, v104
	v_exp_f32_e32 v105, v105
	v_exp_f32_e32 v106, v106
	v_add_f32_e32 v144, v104, v105
	v_exp_f32_e32 v107, v107
	v_exp_f32_e32 v108, v108
	v_add_f32_e32 v144, v144, v106
	v_exp_f32_e32 v109, v109
	v_add_f32_e32 v144, v144, v107
	v_exp_f32_e32 v110, v110
	v_add_f32_e32 v144, v144, v108
	v_exp_f32_e32 v111, v111
	v_add_f32_e32 v144, v144, v109
	v_cvt_pk_bf16_f32 v104, v104, v105
	v_add_f32_e32 v144, v144, v110
	v_cvt_pk_bf16_f32 v105, v106, v107
	v_cvt_pk_bf16_f32 v106, v108, v109
	v_cvt_pk_bf16_f32 v107, v110, v111
	v_add_f32_e32 v144, v144, v111
	v_add_f32_e32 v131, v131, v144
	v_exp_f32_e32 v112, v112
	v_exp_f32_e32 v113, v113
	v_exp_f32_e32 v114, v114
	v_add_f32_e32 v144, v112, v113
	v_exp_f32_e32 v115, v115
	v_exp_f32_e32 v116, v116
	v_add_f32_e32 v144, v144, v114
	v_exp_f32_e32 v117, v117
	v_add_f32_e32 v144, v144, v115
	v_exp_f32_e32 v118, v118
	v_add_f32_e32 v144, v144, v116
	v_exp_f32_e32 v119, v119
	v_add_f32_e32 v144, v144, v117
	v_cvt_pk_bf16_f32 v112, v112, v113
	v_add_f32_e32 v144, v144, v118
	v_cvt_pk_bf16_f32 v113, v114, v115
	v_cvt_pk_bf16_f32 v114, v116, v117
	v_cvt_pk_bf16_f32 v115, v118, v119
	v_add_f32_e32 v144, v144, v119
	v_add_f32_e32 v130, v130, v144
	v_exp_f32_e32 v136, v136
	v_exp_f32_e32 v137, v137
	v_exp_f32_e32 v138, v138
	v_add_f32_e32 v144, v136, v137
	v_exp_f32_e32 v139, v139
	v_exp_f32_e32 v140, v140
	v_add_f32_e32 v144, v144, v138
	v_exp_f32_e32 v141, v141
	v_add_f32_e32 v144, v144, v139
	v_exp_f32_e32 v142, v142
	v_add_f32_e32 v144, v144, v140
	v_exp_f32_e32 v143, v143
	v_add_f32_e32 v144, v144, v141
	v_cvt_pk_bf16_f32 v136, v136, v137
	v_add_f32_e32 v144, v144, v142
	v_cvt_pk_bf16_f32 v137, v138, v139
	v_cvt_pk_bf16_f32 v138, v140, v141
	v_cvt_pk_bf16_f32 v139, v142, v143
	v_add_f32_e32 v144, v144, v143
	v_add_f32_e32 v129, v129, v144
	v_exp_f32_e32 v176, v176
	v_exp_f32_e32 v177, v177
	v_exp_f32_e32 v178, v178
	v_add_f32_e32 v144, v176, v177
	v_exp_f32_e32 v179, v179
	v_exp_f32_e32 v232, v232
	v_add_f32_e32 v144, v144, v178
	v_exp_f32_e32 v233, v233
	v_add_f32_e32 v144, v144, v179
	v_exp_f32_e32 v234, v234
	v_add_f32_e32 v144, v144, v232
	v_exp_f32_e32 v235, v235
	v_add_f32_e32 v144, v144, v233
	v_cvt_pk_bf16_f32 v176, v176, v177
	v_add_f32_e32 v144, v144, v234
	v_cvt_pk_bf16_f32 v177, v178, v179
	v_cvt_pk_bf16_f32 v178, v232, v233
	v_cvt_pk_bf16_f32 v179, v234, v235
	v_add_f32_e32 v144, v144, v235
	v_add_f32_e32 v128, v128, v144
	s_waitcnt lgkmcnt(4)
	v_mfma_f32_16x16x32_bf16 v[64:67], v[216:219], v[104:107], v[64:67]
	v_mfma_f32_16x16x32_bf16 v[60:63], v[220:223], v[104:107], v[60:63]
	v_mfma_f32_16x16x32_bf16 v[56:59], v[224:227], v[104:107], v[56:59]
	v_mfma_f32_16x16x32_bf16 v[52:55], v[228:231], v[104:107], v[52:55]
	v_mfma_f32_16x16x32_bf16 v[48:51], v[216:219], v[112:115], v[48:51]
	v_mfma_f32_16x16x32_bf16 v[44:47], v[220:223], v[112:115], v[44:47]
	v_mfma_f32_16x16x32_bf16 v[40:43], v[224:227], v[112:115], v[40:43]
	v_mfma_f32_16x16x32_bf16 v[36:39], v[228:231], v[112:115], v[36:39]
	v_mfma_f32_16x16x32_bf16 v[72:75], v[216:219], v[136:139], v[72:75]
	v_mfma_f32_16x16x32_bf16 v[84:87], v[220:223], v[136:139], v[84:87]
	v_mfma_f32_16x16x32_bf16 v[88:91], v[224:227], v[136:139], v[88:91]
	v_mfma_f32_16x16x32_bf16 v[96:99], v[228:231], v[136:139], v[96:99]
	v_mfma_f32_16x16x32_bf16 v[68:71], v[216:219], v[176:179], v[68:71]
	v_mfma_f32_16x16x32_bf16 v[76:79], v[220:223], v[176:179], v[76:79]
	v_mfma_f32_16x16x32_bf16 v[80:83], v[224:227], v[176:179], v[80:83]
	v_mfma_f32_16x16x32_bf16 v[92:95], v[228:231], v[176:179], v[92:95]
	s_waitcnt lgkmcnt(0)
; #define LAS __attribute__((address_space(3)))
; __device__ __forceinline__ s16x4 vtr(const LAS unsigned char* p) { return __builtin_bit_cast(s16x4, __builtin_amdgcn_ds_read_tr16_b64_v4i16((LAS v4i16_t*)p)); }
; __device__ __forceinline__ bf16x8 cat8(s16x4 a, s16x4 b) { return (bf16x8){a[0], a[1], a[2], a[3], b[0], b[1], b[2], b[3]}; }
; __device__ __forceinline__ bf16x8 pack8(const f32x4& a, const f32x4& b) { u32x4 w; w.x = pkbf(a[0], a[1]); w.y = pkbf(a[2], a[3]); w.z = pkbf(b[0], b[1]); w.w = pkbf(b[2], b[3]); return __builtin_bit_cast(bf16x8, w); }
;     ...
; #pragma unroll
;     for (int gh = 0; gh < 4 / GPB; ++gh) {
;         f32x4 S[GPB][4];
; #pragma unroll
;         for (int kb = 0; kb < 4; ++kb) {
;             const bf16x8 kf0 = *(const LAS bf16x8*)(kb0 + (16 * kb) * 128 + kx0), kf1 = *(const LAS bf16x8*)(kb0 + (16 * kb) * 128 + kx1);
; #pragma unroll
;             for (int gi = 0; gi < GPB; ++gi) { S[gi][kb] = __builtin_amdgcn_mfma_f32_16x16x32_bf16(kf0, qf[GPB * gh + gi][0], cinit, 0, 0, 0);
;                 S[gi][kb] = __builtin_amdgcn_mfma_f32_16x16x32_bf16(kf1, qf[GPB * gh + gi][1], S[gi][kb], 0, 0, 0); } }
;         bf16x8 pf[GPB][2];
; #pragma unroll
;         for (int gi = 0; gi < GPB; ++gi) {
;             if (MASK) {
; #pragma unroll
;                 for (int kb = 0; kb < 4; ++kb)
; #pragma unroll
;                     for (int i = 0; i < 4; ++i) { const int rel = rel0 + 16 * kb + 4 * g + i; S[gi][kb][i] = ((unsigned)(rel + 128) > 256u) ? NEGBIG : S[gi][kb][i]; }
;             }
;             ls[GPB * gh + gi] += exp_step<4>(S[gi]);
;             pf[gi][0] = pack8(S[gi][0], S[gi][1]); pf[gi][1] = pack8(S[gi][2], S[gi][3]);
;         }
; #pragma unroll
;         for (int kc = 0; kc < 2; ++kc)
; #pragma unroll
;             for (int db = 0; db < 4; ++db) {
;                 const LAS unsigned char* va = vrow + ((db ^ swz) << 5) + (32 * kc) * 128;
;                 const bf16x8 vf = cat8(vtr(va), vtr(va + 16 * 128));
; #pragma unroll
;                 for (int gi = 0; gi < GPB; ++gi) O[GPB * gh + gi][db] = __builtin_amdgcn_mfma_f32_16x16x32_bf16(vf, pf[gi][kc], O[GPB * gh + gi][db], 0, 0, 0);
;             }
; __device__ __forceinline__ void swa_phase(LAS unsigned char* lds, const bf16_t* Q, const bf16_t* K, const bf16_t* V, bf16_t* Ob, const float* sink, float negb) {
;     ...
;             ring_wait<2>();
	v_mfma_f32_16x16x32_bf16 v[104:107], v[160:163], v[4:7], v[0:3]
	v_mfma_f32_16x16x32_bf16 v[108:111], v[168:171], v[4:7], v[0:3]
	v_mfma_f32_16x16x32_bf16 v[112:115], v[160:163], v[8:11], v[0:3]
	v_mfma_f32_16x16x32_bf16 v[116:119], v[168:171], v[8:11], v[0:3]
	v_mfma_f32_16x16x32_bf16 v[136:139], v[160:163], v[20:23], v[0:3]
	v_mfma_f32_16x16x32_bf16 v[140:143], v[168:171], v[20:23], v[0:3]
	v_mfma_f32_16x16x32_bf16 v[176:179], v[160:163], v[28:31], v[0:3]
	v_mfma_f32_16x16x32_bf16 v[232:235], v[168:171], v[28:31], v[0:3]
	v_mfma_f32_16x16x32_bf16 v[104:107], v[164:167], v[12:15], v[104:107]
	v_mfma_f32_16x16x32_bf16 v[108:111], v[172:175], v[12:15], v[108:111]
	v_mfma_f32_16x16x32_bf16 v[112:115], v[164:167], v[16:19], v[112:115]
	v_mfma_f32_16x16x32_bf16 v[116:119], v[172:175], v[16:19], v[116:119]
	v_mfma_f32_16x16x32_bf16 v[136:139], v[164:167], v[24:27], v[136:139]
	v_mfma_f32_16x16x32_bf16 v[140:143], v[172:175], v[24:27], v[140:143]
	v_mfma_f32_16x16x32_bf16 v[176:179], v[164:167], v[32:35], v[176:179]
	v_mfma_f32_16x16x32_bf16 v[232:235], v[172:175], v[32:35], v[232:235]
	ds_read_b64_tr_b16 v[216:217], v103 offset:12288
	ds_read_b64_tr_b16 v[218:219], v103 offset:14336
	ds_read_b64_tr_b16 v[220:221], v133 offset:12288
	ds_read_b64_tr_b16 v[222:223], v133 offset:14336
	ds_read_b64_tr_b16 v[224:225], v134 offset:12288
	ds_read_b64_tr_b16 v[226:227], v134 offset:14336
	ds_read_b64_tr_b16 v[228:229], v135 offset:12288
	ds_read_b64_tr_b16 v[230:231], v135 offset:14336
	v_exp_f32_e32 v104, v104
	v_exp_f32_e32 v105, v105
	v_exp_f32_e32 v106, v106
	v_add_f32_e32 v144, v104, v105
	v_exp_f32_e32 v107, v107
	v_exp_f32_e32 v108, v108
	v_add_f32_e32 v144, v144, v106
	v_exp_f32_e32 v109, v109
	v_add_f32_e32 v144, v144, v107
	v_exp_f32_e32 v110, v110
	v_add_f32_e32 v144, v144, v108
	v_exp_f32_e32 v111, v111
	v_add_f32_e32 v144, v144, v109
	v_cvt_pk_bf16_f32 v104, v104, v105
	v_add_f32_e32 v144, v144, v110
	v_cvt_pk_bf16_f32 v105, v106, v107
	v_cvt_pk_bf16_f32 v106, v108, v109
	v_cvt_pk_bf16_f32 v107, v110, v111
	v_add_f32_e32 v144, v144, v111
	v_add_f32_e32 v131, v131, v144
	v_exp_f32_e32 v112, v112
	v_exp_f32_e32 v113, v113
	v_exp_f32_e32 v114, v114
	v_add_f32_e32 v144, v112, v113
	v_exp_f32_e32 v115, v115
	v_exp_f32_e32 v116, v116
	v_add_f32_e32 v144, v144, v114
	v_exp_f32_e32 v117, v117
	v_add_f32_e32 v144, v144, v115
	v_exp_f32_e32 v118, v118
	v_add_f32_e32 v144, v144, v116
	v_exp_f32_e32 v119, v119
	v_add_f32_e32 v144, v144, v117
	v_cvt_pk_bf16_f32 v112, v112, v113
	v_add_f32_e32 v144, v144, v118
	v_cvt_pk_bf16_f32 v113, v114, v115
	v_cvt_pk_bf16_f32 v114, v116, v117
	v_cvt_pk_bf16_f32 v115, v118, v119
	v_add_f32_e32 v144, v144, v119
	v_add_f32_e32 v130, v130, v144
	v_exp_f32_e32 v136, v136
	v_exp_f32_e32 v137, v137
	v_exp_f32_e32 v138, v138
	v_add_f32_e32 v144, v136, v137
	v_exp_f32_e32 v139, v139
	v_exp_f32_e32 v140, v140
	v_add_f32_e32 v144, v144, v138
	v_exp_f32_e32 v141, v141
	v_add_f32_e32 v144, v144, v139
	v_exp_f32_e32 v142, v142
	v_add_f32_e32 v144, v144, v140
	v_exp_f32_e32 v143, v143
	v_add_f32_e32 v144, v144, v141
	v_cvt_pk_bf16_f32 v136, v136, v137
	v_add_f32_e32 v144, v144, v142
	v_cvt_pk_bf16_f32 v137, v138, v139
	v_cvt_pk_bf16_f32 v138, v140, v141
	v_cvt_pk_bf16_f32 v139, v142, v143
	v_add_f32_e32 v144, v144, v143
	v_add_f32_e32 v129, v129, v144
	v_exp_f32_e32 v176, v176
	v_exp_f32_e32 v177, v177
	v_exp_f32_e32 v178, v178
	v_add_f32_e32 v144, v176, v177
	v_exp_f32_e32 v179, v179
	v_exp_f32_e32 v232, v232
	v_add_f32_e32 v144, v144, v178
	v_exp_f32_e32 v233, v233
	v_add_f32_e32 v144, v144, v179
	v_exp_f32_e32 v234, v234
	v_add_f32_e32 v144, v144, v232
	v_exp_f32_e32 v235, v235
	v_add_f32_e32 v144, v144, v233
	v_cvt_pk_bf16_f32 v176, v176, v177
	v_add_f32_e32 v144, v144, v234
	v_cvt_pk_bf16_f32 v177, v178, v179
	v_cvt_pk_bf16_f32 v178, v232, v233
	v_cvt_pk_bf16_f32 v179, v234, v235
	v_add_f32_e32 v144, v144, v235
	v_add_f32_e32 v128, v128, v144
	s_waitcnt lgkmcnt(0)
	v_mfma_f32_16x16x32_bf16 v[64:67], v[216:219], v[104:107], v[64:67]
	v_mfma_f32_16x16x32_bf16 v[60:63], v[220:223], v[104:107], v[60:63]
	v_mfma_f32_16x16x32_bf16 v[56:59], v[224:227], v[104:107], v[56:59]
	v_mfma_f32_16x16x32_bf16 v[52:55], v[228:231], v[104:107], v[52:55]
	v_mfma_f32_16x16x32_bf16 v[48:51], v[216:219], v[112:115], v[48:51]
	v_mfma_f32_16x16x32_bf16 v[44:47], v[220:223], v[112:115], v[44:47]
	v_mfma_f32_16x16x32_bf16 v[40:43], v[224:227], v[112:115], v[40:43]
	v_mfma_f32_16x16x32_bf16 v[36:39], v[228:231], v[112:115], v[36:39]
	v_mfma_f32_16x16x32_bf16 v[72:75], v[216:219], v[136:139], v[72:75]
	v_mfma_f32_16x16x32_bf16 v[84:87], v[220:223], v[136:139], v[84:87]
	v_mfma_f32_16x16x32_bf16 v[88:91], v[224:227], v[136:139], v[88:91]
	v_mfma_f32_16x16x32_bf16 v[96:99], v[228:231], v[136:139], v[96:99]
	v_mfma_f32_16x16x32_bf16 v[68:71], v[216:219], v[176:179], v[68:71]
	v_mfma_f32_16x16x32_bf16 v[76:79], v[220:223], v[176:179], v[76:79]
	v_mfma_f32_16x16x32_bf16 v[80:83], v[224:227], v[176:179], v[80:83]
	v_mfma_f32_16x16x32_bf16 v[92:95], v[228:231], v[176:179], v[92:95]
	s_addk_i32 s1, 0x4000
	s_add_u32 s7, s7, 64
	s_addc_u32 s8, s8, 0
	s_add_i32 s6, s6, 1
	s_waitcnt vmcnt(4)
	s_barrier
; #define LAS __attribute__((address_space(3)))
; __device__ __forceinline__ s16x4 vtr(const LAS unsigned char* p) { return __builtin_bit_cast(s16x4, __builtin_amdgcn_ds_read_tr16_b64_v4i16((LAS v4i16_t*)p)); }
; __device__ __forceinline__ bf16x8 cat8(s16x4 a, s16x4 b) { return (bf16x8){a[0], a[1], a[2], a[3], b[0], b[1], b[2], b[3]}; }
;     ...
; #pragma unroll
;     for (int gh = 0; gh < 4 / GPB; ++gh) {
;         f32x4 S[GPB][4];
; #pragma unroll
;         for (int kb = 0; kb < 4; ++kb) {
;             const bf16x8 kf0 = *(const LAS bf16x8*)(kb0 + (16 * kb) * 128 + kx0), kf1 = *(const LAS bf16x8*)(kb0 + (16 * kb) * 128 + kx1);
; #pragma unroll
;             for (int gi = 0; gi < GPB; ++gi) { S[gi][kb] = __builtin_amdgcn_mfma_f32_16x16x32_bf16(kf0, qf[GPB * gh + gi][0], cinit, 0, 0, 0);
;                 S[gi][kb] = __builtin_amdgcn_mfma_f32_16x16x32_bf16(kf1, qf[GPB * gh + gi][1], S[gi][kb], 0, 0, 0); } }
;         bf16x8 pf[GPB][2];
; #pragma unroll
;         for (int gi = 0; gi < GPB; ++gi) {
;             if (MASK) {
; #pragma unroll
;                 for (int kb = 0; kb < 4; ++kb)
; #pragma unroll
;                     for (int i = 0; i < 4; ++i) { const int rel = rel0 + 16 * kb + 4 * g + i; S[gi][kb][i] = ((unsigned)(rel + 128) > 256u) ? NEGBIG : S[gi][kb][i]; }
;             }
;             ls[GPB * gh + gi] += exp_step<4>(S[gi]);
;             pf[gi][0] = pack8(S[gi][0], S[gi][1]); pf[gi][1] = pack8(S[gi][2], S[gi][3]);
;         }
; #pragma unroll
;         for (int kc = 0; kc < 2; ++kc)
; #pragma unroll
;             for (int db = 0; db < 4; ++db) {
;                 const LAS unsigned char* va = vrow + ((db ^ swz) << 5) + (32 * kc) * 128;
;                 const bf16x8 vf = cat8(vtr(va), vtr(va + 16 * 128));
; #pragma unroll
;                 for (int gi = 0; gi < GPB; ++gi) O[GPB * gh + gi][db] = __builtin_amdgcn_mfma_f32_16x16x32_bf16(vf, pf[gi][kc], O[GPB * gh + gi][db], 0, 0, 0);
;             }
; __device__ __forceinline__ void swa_phase(LAS unsigned char* lds, const bf16_t* Q, const bf16_t* K, const bf16_t* V, bf16_t* Ob, const float* sink, float negb) {
;     ...
;             dma_tile<1>(lds + ((t + 3) & 3) * SW_BUF, K, V, SW_ROW0(t + 3), 256, dl, w);
;             const LAS unsigned char* buf = lds + (t & 3) * SW_BUF;
;             full_tile<0, 2, 2>(O, ls, qf, negb, buf, buf + 8192, lane, 0);
;             ring_wait<2>();
	s_cmp_lt_u32 s6, s46
	s_cselect_b32 s11, s8, 0
	s_cselect_b32 s10, s7, s82
	s_lshl_b64 s[10:11], s[10:11], 9
	s_add_u32 s12, s67, s10
	s_addc_u32 s13, s4, s11
	s_add_u32 s10, s5, s10
	s_addc_u32 s11, s58, s11
	s_add_i32 s9, s40, s1
	s_mov_b32 s15, m0
	s_mov_b32 m0, s9
	s_nop 0
	global_load_lds_dwordx4 v212, s[12:13]
	s_mov_b32 m0, s15
	s_add_i32 s14, s9, 0x2000
	s_mov_b32 s9, m0
	s_mov_b32 m0, s14
	s_nop 0
	global_load_lds_dwordx4 v213, s[10:11]
	s_mov_b32 m0, s9
	s_add_i32 s34, s1, 0x4000
	v_add_u32_e32 v100, s34, v191
	v_add3_u32 v135, s34, v203, v198
	v_add_u32_e32 v102, v100, v193
	v_add_u32_e32 v100, v100, v192
	ds_read_b128 v[160:163], v100
	ds_read_b128 v[164:167], v102
	ds_read_b128 v[168:171], v100 offset:2048
	ds_read_b128 v[172:175], v102 offset:2048
	v_add_u32_e32 v103, v135, v199
	v_add_u32_e32 v133, v135, v200
	v_add_u32_e32 v134, v135, v201
	v_add_u32_e32 v135, v135, v202
	s_waitcnt lgkmcnt(0)
	v_mfma_f32_16x16x32_bf16 v[104:107], v[160:163], v[4:7], v[0:3]
	v_mfma_f32_16x16x32_bf16 v[108:111], v[168:171], v[4:7], v[0:3]
	v_mfma_f32_16x16x32_bf16 v[112:115], v[160:163], v[8:11], v[0:3]
	v_mfma_f32_16x16x32_bf16 v[116:119], v[168:171], v[8:11], v[0:3]
	v_mfma_f32_16x16x32_bf16 v[136:139], v[160:163], v[20:23], v[0:3]
	v_mfma_f32_16x16x32_bf16 v[140:143], v[168:171], v[20:23], v[0:3]
	v_mfma_f32_16x16x32_bf16 v[176:179], v[160:163], v[28:31], v[0:3]
	v_mfma_f32_16x16x32_bf16 v[232:235], v[168:171], v[28:31], v[0:3]
	v_mfma_f32_16x16x32_bf16 v[104:107], v[164:167], v[12:15], v[104:107]
	v_mfma_f32_16x16x32_bf16 v[108:111], v[172:175], v[12:15], v[108:111]
	v_mfma_f32_16x16x32_bf16 v[112:115], v[164:167], v[16:19], v[112:115]
	v_mfma_f32_16x16x32_bf16 v[116:119], v[172:175], v[16:19], v[116:119]
	v_mfma_f32_16x16x32_bf16 v[136:139], v[164:167], v[24:27], v[136:139]
	v_mfma_f32_16x16x32_bf16 v[140:143], v[172:175], v[24:27], v[140:143]
	v_mfma_f32_16x16x32_bf16 v[176:179], v[164:167], v[32:35], v[176:179]
	v_mfma_f32_16x16x32_bf16 v[232:235], v[172:175], v[32:35], v[232:235]
	ds_read_b64_tr_b16 v[216:217], v103 offset:8192
	ds_read_b64_tr_b16 v[218:219], v103 offset:10240
	ds_read_b64_tr_b16 v[220:221], v133 offset:8192
	ds_read_b64_tr_b16 v[222:223], v133 offset:10240
	ds_read_b64_tr_b16 v[224:225], v134 offset:8192
	ds_read_b64_tr_b16 v[226:227], v134 offset:10240
	ds_read_b64_tr_b16 v[228:229], v135 offset:8192
	ds_read_b64_tr_b16 v[230:231], v135 offset:10240
	ds_read_b128 v[160:163], v100 offset:4096
	ds_read_b128 v[164:167], v102 offset:4096
	ds_read_b128 v[168:171], v100 offset:6144
	ds_read_b128 v[172:175], v102 offset:6144
	v_exp_f32_e32 v104, v104
	v_exp_f32_e32 v105, v105
	v_exp_f32_e32 v106, v106
	v_add_f32_e32 v144, v104, v105
	v_exp_f32_e32 v107, v107
	v_exp_f32_e32 v108, v108
	v_add_f32_e32 v144, v144, v106
	v_exp_f32_e32 v109, v109
	v_add_f32_e32 v144, v144, v107
	v_exp_f32_e32 v110, v110
	v_add_f32_e32 v144, v144, v108
	v_exp_f32_e32 v111, v111
	v_add_f32_e32 v144, v144, v109
	v_cvt_pk_bf16_f32 v104, v104, v105
	v_add_f32_e32 v144, v144, v110
	v_cvt_pk_bf16_f32 v105, v106, v107
	v_cvt_pk_bf16_f32 v106, v108, v109
	v_cvt_pk_bf16_f32 v107, v110, v111
	v_add_f32_e32 v144, v144, v111
	v_add_f32_e32 v131, v131, v144
	v_exp_f32_e32 v112, v112
	v_exp_f32_e32 v113, v113
	v_exp_f32_e32 v114, v114
	v_add_f32_e32 v144, v112, v113
	v_exp_f32_e32 v115, v115
	v_exp_f32_e32 v116, v116
	v_add_f32_e32 v144, v144, v114
	v_exp_f32_e32 v117, v117
	v_add_f32_e32 v144, v144, v115
	v_exp_f32_e32 v118, v118
	v_add_f32_e32 v144, v144, v116
	v_exp_f32_e32 v119, v119
	v_add_f32_e32 v144, v144, v117
	v_cvt_pk_bf16_f32 v112, v112, v113
	v_add_f32_e32 v144, v144, v118
	v_cvt_pk_bf16_f32 v113, v114, v115
	v_cvt_pk_bf16_f32 v114, v116, v117
	v_cvt_pk_bf16_f32 v115, v118, v119
	v_add_f32_e32 v144, v144, v119
	v_add_f32_e32 v130, v130, v144
	v_exp_f32_e32 v136, v136
	v_exp_f32_e32 v137, v137
	v_exp_f32_e32 v138, v138
	v_add_f32_e32 v144, v136, v137
	v_exp_f32_e32 v139, v139
	v_exp_f32_e32 v140, v140
	v_add_f32_e32 v144, v144, v138
	v_exp_f32_e32 v141, v141
	v_add_f32_e32 v144, v144, v139
	v_exp_f32_e32 v142, v142
	v_add_f32_e32 v144, v144, v140
	v_exp_f32_e32 v143, v143
	v_add_f32_e32 v144, v144, v141
	v_cvt_pk_bf16_f32 v136, v136, v137
	v_add_f32_e32 v144, v144, v142
	v_cvt_pk_bf16_f32 v137, v138, v139
	v_cvt_pk_bf16_f32 v138, v140, v141
	v_cvt_pk_bf16_f32 v139, v142, v143
	v_add_f32_e32 v144, v144, v143
	v_add_f32_e32 v129, v129, v144
	v_exp_f32_e32 v176, v176
	v_exp_f32_e32 v177, v177
	v_exp_f32_e32 v178, v178
	v_add_f32_e32 v144, v176, v177
	v_exp_f32_e32 v179, v179
	v_exp_f32_e32 v232, v232
	v_add_f32_e32 v144, v144, v178
	v_exp_f32_e32 v233, v233
	v_add_f32_e32 v144, v144, v179
	v_exp_f32_e32 v234, v234
	v_add_f32_e32 v144, v144, v232
	v_exp_f32_e32 v235, v235
	v_add_f32_e32 v144, v144, v233
	v_cvt_pk_bf16_f32 v176, v176, v177
	v_add_f32_e32 v144, v144, v234
	v_cvt_pk_bf16_f32 v177, v178, v179
	v_cvt_pk_bf16_f32 v178, v232, v233
	v_cvt_pk_bf16_f32 v179, v234, v235
	v_add_f32_e32 v144, v144, v235
	v_add_f32_e32 v128, v128, v144
	s_waitcnt lgkmcnt(4)
	v_mfma_f32_16x16x32_bf16 v[64:67], v[216:219], v[104:107], v[64:67]
	v_mfma_f32_16x16x32_bf16 v[60:63], v[220:223], v[104:107], v[60:63]
	v_mfma_f32_16x16x32_bf16 v[56:59], v[224:227], v[104:107], v[56:59]
	v_mfma_f32_16x16x32_bf16 v[52:55], v[228:231], v[104:107], v[52:55]
	v_mfma_f32_16x16x32_bf16 v[48:51], v[216:219], v[112:115], v[48:51]
	v_mfma_f32_16x16x32_bf16 v[44:47], v[220:223], v[112:115], v[44:47]
	v_mfma_f32_16x16x32_bf16 v[40:43], v[224:227], v[112:115], v[40:43]
	v_mfma_f32_16x16x32_bf16 v[36:39], v[228:231], v[112:115], v[36:39]
	v_mfma_f32_16x16x32_bf16 v[72:75], v[216:219], v[136:139], v[72:75]
	v_mfma_f32_16x16x32_bf16 v[84:87], v[220:223], v[136:139], v[84:87]
	v_mfma_f32_16x16x32_bf16 v[88:91], v[224:227], v[136:139], v[88:91]
	v_mfma_f32_16x16x32_bf16 v[96:99], v[228:231], v[136:139], v[96:99]
	v_mfma_f32_16x16x32_bf16 v[68:71], v[216:219], v[176:179], v[68:71]
	v_mfma_f32_16x16x32_bf16 v[76:79], v[220:223], v[176:179], v[76:79]
	v_mfma_f32_16x16x32_bf16 v[80:83], v[224:227], v[176:179], v[80:83]
	v_mfma_f32_16x16x32_bf16 v[92:95], v[228:231], v[176:179], v[92:95]
	s_waitcnt lgkmcnt(0)
; #define LAS __attribute__((address_space(3)))
; __device__ __forceinline__ s16x4 vtr(const LAS unsigned char* p) { return __builtin_bit_cast(s16x4, __builtin_amdgcn_ds_read_tr16_b64_v4i16((LAS v4i16_t*)p)); }
; __device__ __forceinline__ bf16x8 cat8(s16x4 a, s16x4 b) { return (bf16x8){a[0], a[1], a[2], a[3], b[0], b[1], b[2], b[3]}; }
; __device__ __forceinline__ bf16x8 pack8(const f32x4& a, const f32x4& b) { u32x4 w; w.x = pkbf(a[0], a[1]); w.y = pkbf(a[2], a[3]); w.z = pkbf(b[0], b[1]); w.w = pkbf(b[2], b[3]); return __builtin_bit_cast(bf16x8, w); }
;     ...
; #pragma unroll
;     for (int gh = 0; gh < 4 / GPB; ++gh) {
;         f32x4 S[GPB][4];
; #pragma unroll
;         for (int kb = 0; kb < 4; ++kb) {
;             const bf16x8 kf0 = *(const LAS bf16x8*)(kb0 + (16 * kb) * 128 + kx0), kf1 = *(const LAS bf16x8*)(kb0 + (16 * kb) * 128 + kx1);
; #pragma unroll
;             for (int gi = 0; gi < GPB; ++gi) { S[gi][kb] = __builtin_amdgcn_mfma_f32_16x16x32_bf16(kf0, qf[GPB * gh + gi][0], cinit, 0, 0, 0);
;                 S[gi][kb] = __builtin_amdgcn_mfma_f32_16x16x32_bf16(kf1, qf[GPB * gh + gi][1], S[gi][kb], 0, 0, 0); } }
;         bf16x8 pf[GPB][2];
; #pragma unroll
;         for (int gi = 0; gi < GPB; ++gi) {
;             if (MASK) {
; #pragma unroll
;                 for (int kb = 0; kb < 4; ++kb)
; #pragma unroll
;                     for (int i = 0; i < 4; ++i) { const int rel = rel0 + 16 * kb + 4 * g + i; S[gi][kb][i] = ((unsigned)(rel + 128) > 256u) ? NEGBIG : S[gi][kb][i]; }
;             }
;             ls[GPB * gh + gi] += exp_step<4>(S[gi]);
;             pf[gi][0] = pack8(S[gi][0], S[gi][1]); pf[gi][1] = pack8(S[gi][2], S[gi][3]);
;         }
; #pragma unroll
;         for (int kc = 0; kc < 2; ++kc)
; #pragma unroll
;             for (int db = 0; db < 4; ++db) {
;                 const LAS unsigned char* va = vrow + ((db ^ swz) << 5) + (32 * kc) * 128;
;                 const bf16x8 vf = cat8(vtr(va), vtr(va + 16 * 128));
; #pragma unroll
;                 for (int gi = 0; gi < GPB; ++gi) O[GPB * gh + gi][db] = __builtin_amdgcn_mfma_f32_16x16x32_bf16(vf, pf[gi][kc], O[GPB * gh + gi][db], 0, 0, 0);
;             }
; __device__ __forceinline__ void swa_phase(LAS unsigned char* lds, const bf16_t* Q, const bf16_t* K, const bf16_t* V, bf16_t* Ob, const float* sink, float negb) {
;     ...
;             ring_wait<2>();
	v_mfma_f32_16x16x32_bf16 v[104:107], v[160:163], v[4:7], v[0:3]
	v_mfma_f32_16x16x32_bf16 v[108:111], v[168:171], v[4:7], v[0:3]
	v_mfma_f32_16x16x32_bf16 v[112:115], v[160:163], v[8:11], v[0:3]
	v_mfma_f32_16x16x32_bf16 v[116:119], v[168:171], v[8:11], v[0:3]
	v_mfma_f32_16x16x32_bf16 v[136:139], v[160:163], v[20:23], v[0:3]
	v_mfma_f32_16x16x32_bf16 v[140:143], v[168:171], v[20:23], v[0:3]
	v_mfma_f32_16x16x32_bf16 v[176:179], v[160:163], v[28:31], v[0:3]
	v_mfma_f32_16x16x32_bf16 v[232:235], v[168:171], v[28:31], v[0:3]
	v_mfma_f32_16x16x32_bf16 v[104:107], v[164:167], v[12:15], v[104:107]
	v_mfma_f32_16x16x32_bf16 v[108:111], v[172:175], v[12:15], v[108:111]
	v_mfma_f32_16x16x32_bf16 v[112:115], v[164:167], v[16:19], v[112:115]
	v_mfma_f32_16x16x32_bf16 v[116:119], v[172:175], v[16:19], v[116:119]
	v_mfma_f32_16x16x32_bf16 v[136:139], v[164:167], v[24:27], v[136:139]
	v_mfma_f32_16x16x32_bf16 v[140:143], v[172:175], v[24:27], v[140:143]
	v_mfma_f32_16x16x32_bf16 v[176:179], v[164:167], v[32:35], v[176:179]
	v_mfma_f32_16x16x32_bf16 v[232:235], v[172:175], v[32:35], v[232:235]
	ds_read_b64_tr_b16 v[216:217], v103 offset:12288
	ds_read_b64_tr_b16 v[218:219], v103 offset:14336
	ds_read_b64_tr_b16 v[220:221], v133 offset:12288
	ds_read_b64_tr_b16 v[222:223], v133 offset:14336
	ds_read_b64_tr_b16 v[224:225], v134 offset:12288
	ds_read_b64_tr_b16 v[226:227], v134 offset:14336
	ds_read_b64_tr_b16 v[228:229], v135 offset:12288
	ds_read_b64_tr_b16 v[230:231], v135 offset:14336
	v_exp_f32_e32 v104, v104
	v_exp_f32_e32 v105, v105
	v_exp_f32_e32 v106, v106
	v_add_f32_e32 v144, v104, v105
	v_exp_f32_e32 v107, v107
	v_exp_f32_e32 v108, v108
	v_add_f32_e32 v144, v144, v106
	v_exp_f32_e32 v109, v109
	v_add_f32_e32 v144, v144, v107
	v_exp_f32_e32 v110, v110
	v_add_f32_e32 v144, v144, v108
	v_exp_f32_e32 v111, v111
	v_add_f32_e32 v144, v144, v109
	v_cvt_pk_bf16_f32 v104, v104, v105
	v_add_f32_e32 v144, v144, v110
	v_cvt_pk_bf16_f32 v105, v106, v107
	v_cvt_pk_bf16_f32 v106, v108, v109
	v_cvt_pk_bf16_f32 v107, v110, v111
	v_add_f32_e32 v144, v144, v111
	v_add_f32_e32 v131, v131, v144
	v_exp_f32_e32 v112, v112
	v_exp_f32_e32 v113, v113
	v_exp_f32_e32 v114, v114
	v_add_f32_e32 v144, v112, v113
	v_exp_f32_e32 v115, v115
	v_exp_f32_e32 v116, v116
	v_add_f32_e32 v144, v144, v114
	v_exp_f32_e32 v117, v117
	v_add_f32_e32 v144, v144, v115
	v_exp_f32_e32 v118, v118
	v_add_f32_e32 v144, v144, v116
	v_exp_f32_e32 v119, v119
	v_add_f32_e32 v144, v144, v117
	v_cvt_pk_bf16_f32 v112, v112, v113
	v_add_f32_e32 v144, v144, v118
	v_cvt_pk_bf16_f32 v113, v114, v115
	v_cvt_pk_bf16_f32 v114, v116, v117
	v_cvt_pk_bf16_f32 v115, v118, v119
	v_add_f32_e32 v144, v144, v119
	v_add_f32_e32 v130, v130, v144
	v_exp_f32_e32 v136, v136
	v_exp_f32_e32 v137, v137
	v_exp_f32_e32 v138, v138
	v_add_f32_e32 v144, v136, v137
	v_exp_f32_e32 v139, v139
	v_exp_f32_e32 v140, v140
	v_add_f32_e32 v144, v144, v138
	v_exp_f32_e32 v141, v141
	v_add_f32_e32 v144, v144, v139
	v_exp_f32_e32 v142, v142
	v_add_f32_e32 v144, v144, v140
	v_exp_f32_e32 v143, v143
	v_add_f32_e32 v144, v144, v141
	v_cvt_pk_bf16_f32 v136, v136, v137
	v_add_f32_e32 v144, v144, v142
	v_cvt_pk_bf16_f32 v137, v138, v139
	v_cvt_pk_bf16_f32 v138, v140, v141
	v_cvt_pk_bf16_f32 v139, v142, v143
	v_add_f32_e32 v144, v144, v143
	v_add_f32_e32 v129, v129, v144
	v_exp_f32_e32 v176, v176
	v_exp_f32_e32 v177, v177
	v_exp_f32_e32 v178, v178
	v_add_f32_e32 v144, v176, v177
	v_exp_f32_e32 v179, v179
	v_exp_f32_e32 v232, v232
	v_add_f32_e32 v144, v144, v178
	v_exp_f32_e32 v233, v233
	v_add_f32_e32 v144, v144, v179
	v_exp_f32_e32 v234, v234
	v_add_f32_e32 v144, v144, v232
	v_exp_f32_e32 v235, v235
	v_add_f32_e32 v144, v144, v233
	v_cvt_pk_bf16_f32 v176, v176, v177
	v_add_f32_e32 v144, v144, v234
	v_cvt_pk_bf16_f32 v177, v178, v179
	v_cvt_pk_bf16_f32 v178, v232, v233
	v_cvt_pk_bf16_f32 v179, v234, v235
	v_add_f32_e32 v144, v144, v235
	v_add_f32_e32 v128, v128, v144
	s_waitcnt lgkmcnt(0)
	v_mfma_f32_16x16x32_bf16 v[64:67], v[216:219], v[104:107], v[64:67]
	v_mfma_f32_16x16x32_bf16 v[60:63], v[220:223], v[104:107], v[60:63]
	v_mfma_f32_16x16x32_bf16 v[56:59], v[224:227], v[104:107], v[56:59]
	v_mfma_f32_16x16x32_bf16 v[52:55], v[228:231], v[104:107], v[52:55]
	v_mfma_f32_16x16x32_bf16 v[48:51], v[216:219], v[112:115], v[48:51]
	v_mfma_f32_16x16x32_bf16 v[44:47], v[220:223], v[112:115], v[44:47]
	v_mfma_f32_16x16x32_bf16 v[40:43], v[224:227], v[112:115], v[40:43]
	v_mfma_f32_16x16x32_bf16 v[36:39], v[228:231], v[112:115], v[36:39]
	v_mfma_f32_16x16x32_bf16 v[72:75], v[216:219], v[136:139], v[72:75]
	v_mfma_f32_16x16x32_bf16 v[84:87], v[220:223], v[136:139], v[84:87]
	v_mfma_f32_16x16x32_bf16 v[88:91], v[224:227], v[136:139], v[88:91]
	v_mfma_f32_16x16x32_bf16 v[96:99], v[228:231], v[136:139], v[96:99]
	v_mfma_f32_16x16x32_bf16 v[68:71], v[216:219], v[176:179], v[68:71]
	v_mfma_f32_16x16x32_bf16 v[76:79], v[220:223], v[176:179], v[76:79]
	v_mfma_f32_16x16x32_bf16 v[80:83], v[224:227], v[176:179], v[80:83]
	v_mfma_f32_16x16x32_bf16 v[92:95], v[228:231], v[176:179], v[92:95]
	s_addk_i32 s1, 0x4000
	s_add_u32 s7, s7, 64
	s_addc_u32 s8, s8, 0
	s_add_i32 s6, s6, 1
	s_waitcnt vmcnt(4)
	s_barrier
; #define LAS __attribute__((address_space(3)))
; __device__ __forceinline__ s16x4 vtr(const LAS unsigned char* p) { return __builtin_bit_cast(s16x4, __builtin_amdgcn_ds_read_tr16_b64_v4i16((LAS v4i16_t*)p)); }
; __device__ __forceinline__ bf16x8 cat8(s16x4 a, s16x4 b) { return (bf16x8){a[0], a[1], a[2], a[3], b[0], b[1], b[2], b[3]}; }
;     ...
; #pragma unroll
;     for (int gh = 0; gh < 4 / GPB; ++gh) {
;         f32x4 S[GPB][4];
; #pragma unroll
;         for (int kb = 0; kb < 4; ++kb) {
;             const bf16x8 kf0 = *(const LAS bf16x8*)(kb0 + (16 * kb) * 128 + kx0), kf1 = *(const LAS bf16x8*)(kb0 + (16 * kb) * 128 + kx1);
; #pragma unroll
;             for (int gi = 0; gi < GPB; ++gi) { S[gi][kb] = __builtin_amdgcn_mfma_f32_16x16x32_bf16(kf0, qf[GPB * gh + gi][0], cinit, 0, 0, 0);
;                 S[gi][kb] = __builtin_amdgcn_mfma_f32_16x16x32_bf16(kf1, qf[GPB * gh + gi][1], S[gi][kb], 0, 0, 0); } }
;         bf16x8 pf[GPB][2];
; #pragma unroll
;         for (int gi = 0; gi < GPB; ++gi) {
;             if (MASK) {
; #pragma unroll
;                 for (int kb = 0; kb < 4; ++kb)
; #pragma unroll
;                     for (int i = 0; i < 4; ++i) { const int rel = rel0 + 16 * kb + 4 * g + i; S[gi][kb][i] = ((unsigned)(rel + 128) > 256u) ? NEGBIG : S[gi][kb][i]; }
;             }
;             ls[GPB * gh + gi] += exp_step<4>(S[gi]);
;             pf[gi][0] = pack8(S[gi][0], S[gi][1]); pf[gi][1] = pack8(S[gi][2], S[gi][3]);
;         }
; #pragma unroll
;         for (int kc = 0; kc < 2; ++kc)
; #pragma unroll
;             for (int db = 0; db < 4; ++db) {
;                 const LAS unsigned char* va = vrow + ((db ^ swz) << 5) + (32 * kc) * 128;
;                 const bf16x8 vf = cat8(vtr(va), vtr(va + 16 * 128));
; #pragma unroll
;                 for (int gi = 0; gi < GPB; ++gi) O[GPB * gh + gi][db] = __builtin_amdgcn_mfma_f32_16x16x32_bf16(vf, pf[gi][kc], O[GPB * gh + gi][db], 0, 0, 0);
;             }
; __device__ __forceinline__ void swa_phase(LAS unsigned char* lds, const bf16_t* Q, const bf16_t* K, const bf16_t* V, bf16_t* Ob, const float* sink, float negb) {
;     ...
;             dma_tile<1>(lds + ((t + 3) & 3) * SW_BUF, K, V, SW_ROW0(t + 3), 256, dl, w);
;             const LAS unsigned char* buf = lds + (t & 3) * SW_BUF;
;             full_tile<0, 2, 2>(O, ls, qf, negb, buf, buf + 8192, lane, 0);
;             ring_wait<2>();
	s_cmp_lt_u32 s6, s46
	s_cselect_b32 s11, s8, 0
	s_cselect_b32 s10, s7, s82
	s_lshl_b64 s[10:11], s[10:11], 9
	s_add_u32 s12, s67, s10
	s_addc_u32 s13, s4, s11
	s_add_u32 s10, s5, s10
	s_addc_u32 s11, s58, s11
	s_add_i32 s9, s40, s1
	s_mov_b32 s15, m0
	s_mov_b32 m0, s9
	s_nop 0
	global_load_lds_dwordx4 v212, s[12:13]
	s_mov_b32 m0, s15
	s_add_i32 s14, s9, 0x2000
	s_mov_b32 s9, m0
	s_mov_b32 m0, s14
	s_nop 0
	global_load_lds_dwordx4 v213, s[10:11]
	s_mov_b32 m0, s9
	s_add_i32 s34, s1, 0x4000
	v_add_u32_e32 v100, s34, v191
	v_add3_u32 v135, s34, v203, v198
	v_add_u32_e32 v102, v100, v193
	v_add_u32_e32 v100, v100, v192
	ds_read_b128 v[160:163], v100
	ds_read_b128 v[164:167], v102
	ds_read_b128 v[168:171], v100 offset:2048
	ds_read_b128 v[172:175], v102 offset:2048
	v_add_u32_e32 v103, v135, v199
	v_add_u32_e32 v133, v135, v200
	v_add_u32_e32 v134, v135, v201
	v_add_u32_e32 v135, v135, v202
	s_waitcnt lgkmcnt(0)
	v_mfma_f32_16x16x32_bf16 v[104:107], v[160:163], v[4:7], v[0:3]
	v_mfma_f32_16x16x32_bf16 v[108:111], v[168:171], v[4:7], v[0:3]
	v_mfma_f32_16x16x32_bf16 v[112:115], v[160:163], v[8:11], v[0:3]
	v_mfma_f32_16x16x32_bf16 v[116:119], v[168:171], v[8:11], v[0:3]
	v_mfma_f32_16x16x32_bf16 v[136:139], v[160:163], v[20:23], v[0:3]
	v_mfma_f32_16x16x32_bf16 v[140:143], v[168:171], v[20:23], v[0:3]
	v_mfma_f32_16x16x32_bf16 v[176:179], v[160:163], v[28:31], v[0:3]
	v_mfma_f32_16x16x32_bf16 v[232:235], v[168:171], v[28:31], v[0:3]
	v_mfma_f32_16x16x32_bf16 v[104:107], v[164:167], v[12:15], v[104:107]
	v_mfma_f32_16x16x32_bf16 v[108:111], v[172:175], v[12:15], v[108:111]
	v_mfma_f32_16x16x32_bf16 v[112:115], v[164:167], v[16:19], v[112:115]
	v_mfma_f32_16x16x32_bf16 v[116:119], v[172:175], v[16:19], v[116:119]
	v_mfma_f32_16x16x32_bf16 v[136:139], v[164:167], v[24:27], v[136:139]
	v_mfma_f32_16x16x32_bf16 v[140:143], v[172:175], v[24:27], v[140:143]
	v_mfma_f32_16x16x32_bf16 v[176:179], v[164:167], v[32:35], v[176:179]
	v_mfma_f32_16x16x32_bf16 v[232:235], v[172:175], v[32:35], v[232:235]
	ds_read_b64_tr_b16 v[216:217], v103 offset:8192
	ds_read_b64_tr_b16 v[218:219], v103 offset:10240
	ds_read_b64_tr_b16 v[220:221], v133 offset:8192
	ds_read_b64_tr_b16 v[222:223], v133 offset:10240
	ds_read_b64_tr_b16 v[224:225], v134 offset:8192
	ds_read_b64_tr_b16 v[226:227], v134 offset:10240
	ds_read_b64_tr_b16 v[228:229], v135 offset:8192
	ds_read_b64_tr_b16 v[230:231], v135 offset:10240
	ds_read_b128 v[160:163], v100 offset:4096
	ds_read_b128 v[164:167], v102 offset:4096
	ds_read_b128 v[168:171], v100 offset:6144
	ds_read_b128 v[172:175], v102 offset:6144
	v_exp_f32_e32 v104, v104
	v_exp_f32_e32 v105, v105
	v_exp_f32_e32 v106, v106
	v_add_f32_e32 v144, v104, v105
	v_exp_f32_e32 v107, v107
	v_exp_f32_e32 v108, v108
	v_add_f32_e32 v144, v144, v106
	v_exp_f32_e32 v109, v109
	v_add_f32_e32 v144, v144, v107
	v_exp_f32_e32 v110, v110
	v_add_f32_e32 v144, v144, v108
	v_exp_f32_e32 v111, v111
	v_add_f32_e32 v144, v144, v109
	v_cvt_pk_bf16_f32 v104, v104, v105
	v_add_f32_e32 v144, v144, v110
	v_cvt_pk_bf16_f32 v105, v106, v107
	v_cvt_pk_bf16_f32 v106, v108, v109
	v_cvt_pk_bf16_f32 v107, v110, v111
	v_add_f32_e32 v144, v144, v111
	v_add_f32_e32 v131, v131, v144
	v_exp_f32_e32 v112, v112
	v_exp_f32_e32 v113, v113
	v_exp_f32_e32 v114, v114
	v_add_f32_e32 v144, v112, v113
	v_exp_f32_e32 v115, v115
	v_exp_f32_e32 v116, v116
	v_add_f32_e32 v144, v144, v114
	v_exp_f32_e32 v117, v117
	v_add_f32_e32 v144, v144, v115
	v_exp_f32_e32 v118, v118
	v_add_f32_e32 v144, v144, v116
	v_exp_f32_e32 v119, v119
	v_add_f32_e32 v144, v144, v117
	v_cvt_pk_bf16_f32 v112, v112, v113
	v_add_f32_e32 v144, v144, v118
	v_cvt_pk_bf16_f32 v113, v114, v115
	v_cvt_pk_bf16_f32 v114, v116, v117
	v_cvt_pk_bf16_f32 v115, v118, v119
	v_add_f32_e32 v144, v144, v119
	v_add_f32_e32 v130, v130, v144
	v_exp_f32_e32 v136, v136
	v_exp_f32_e32 v137, v137
	v_exp_f32_e32 v138, v138
	v_add_f32_e32 v144, v136, v137
	v_exp_f32_e32 v139, v139
	v_exp_f32_e32 v140, v140
	v_add_f32_e32 v144, v144, v138
	v_exp_f32_e32 v141, v141
	v_add_f32_e32 v144, v144, v139
	v_exp_f32_e32 v142, v142
	v_add_f32_e32 v144, v144, v140
	v_exp_f32_e32 v143, v143
	v_add_f32_e32 v144, v144, v141
	v_cvt_pk_bf16_f32 v136, v136, v137
	v_add_f32_e32 v144, v144, v142
	v_cvt_pk_bf16_f32 v137, v138, v139
	v_cvt_pk_bf16_f32 v138, v140, v141
	v_cvt_pk_bf16_f32 v139, v142, v143
	v_add_f32_e32 v144, v144, v143
	v_add_f32_e32 v129, v129, v144
	v_exp_f32_e32 v176, v176
	v_exp_f32_e32 v177, v177
	v_exp_f32_e32 v178, v178
	v_add_f32_e32 v144, v176, v177
	v_exp_f32_e32 v179, v179
	v_exp_f32_e32 v232, v232
	v_add_f32_e32 v144, v144, v178
	v_exp_f32_e32 v233, v233
	v_add_f32_e32 v144, v144, v179
	v_exp_f32_e32 v234, v234
	v_add_f32_e32 v144, v144, v232
	v_exp_f32_e32 v235, v235
	v_add_f32_e32 v144, v144, v233
	v_cvt_pk_bf16_f32 v176, v176, v177
	v_add_f32_e32 v144, v144, v234
	v_cvt_pk_bf16_f32 v177, v178, v179
	v_cvt_pk_bf16_f32 v178, v232, v233
	v_cvt_pk_bf16_f32 v179, v234, v235
	v_add_f32_e32 v144, v144, v235
	v_add_f32_e32 v128, v128, v144
	s_waitcnt lgkmcnt(4)
	v_mfma_f32_16x16x32_bf16 v[64:67], v[216:219], v[104:107], v[64:67]
	v_mfma_f32_16x16x32_bf16 v[60:63], v[220:223], v[104:107], v[60:63]
	v_mfma_f32_16x16x32_bf16 v[56:59], v[224:227], v[104:107], v[56:59]
	v_mfma_f32_16x16x32_bf16 v[52:55], v[228:231], v[104:107], v[52:55]
	v_mfma_f32_16x16x32_bf16 v[48:51], v[216:219], v[112:115], v[48:51]
	v_mfma_f32_16x16x32_bf16 v[44:47], v[220:223], v[112:115], v[44:47]
	v_mfma_f32_16x16x32_bf16 v[40:43], v[224:227], v[112:115], v[40:43]
	v_mfma_f32_16x16x32_bf16 v[36:39], v[228:231], v[112:115], v[36:39]
	v_mfma_f32_16x16x32_bf16 v[72:75], v[216:219], v[136:139], v[72:75]
	v_mfma_f32_16x16x32_bf16 v[84:87], v[220:223], v[136:139], v[84:87]
	v_mfma_f32_16x16x32_bf16 v[88:91], v[224:227], v[136:139], v[88:91]
	v_mfma_f32_16x16x32_bf16 v[96:99], v[228:231], v[136:139], v[96:99]
	v_mfma_f32_16x16x32_bf16 v[68:71], v[216:219], v[176:179], v[68:71]
	v_mfma_f32_16x16x32_bf16 v[76:79], v[220:223], v[176:179], v[76:79]
	v_mfma_f32_16x16x32_bf16 v[80:83], v[224:227], v[176:179], v[80:83]
	v_mfma_f32_16x16x32_bf16 v[92:95], v[228:231], v[176:179], v[92:95]
	s_waitcnt lgkmcnt(0)
; #define LAS __attribute__((address_space(3)))
;     ...
; #pragma unroll
;     for (int gh = 0; gh < 4 / GPB; ++gh) {
;         f32x4 S[GPB][4];
; #pragma unroll
;         for (int kb = 0; kb < 4; ++kb) {
;             const bf16x8 kf0 = *(const LAS bf16x8*)(kb0 + (16 * kb) * 128 + kx0), kf1 = *(const LAS bf16x8*)(kb0 + (16 * kb) * 128 + kx1);
; #pragma unroll
;             for (int gi = 0; gi < GPB; ++gi) { S[gi][kb] = __builtin_amdgcn_mfma_f32_16x16x32_bf16(kf0, qf[GPB * gh + gi][0], cinit, 0, 0, 0);
;                 S[gi][kb] = __builtin_amdgcn_mfma_f32_16x16x32_bf16(kf1, qf[GPB * gh + gi][1], S[gi][kb], 0, 0, 0); } }
;         bf16x8 pf[GPB][2];
; #pragma unroll
;         for (int gi = 0; gi < GPB; ++gi) {
;             if (MASK) {
; #pragma unroll
;                 for (int kb = 0; kb < 4; ++kb)
; #pragma unroll
;                     for (int i = 0; i < 4; ++i) { const int rel = rel0 + 16 * kb + 4 * g + i; S[gi][kb][i] = ((unsigned)(rel + 128) > 256u) ? NEGBIG : S[gi][kb][i]; }
;             }
;             ls[GPB * gh + gi] += exp_step<4>(S[gi]);
;             pf[gi][0] = pack8(S[gi][0], S[gi][1]); pf[gi][1] = pack8(S[gi][2], S[gi][3]);
;         }
; #pragma unroll
;         for (int kc = 0; kc < 2; ++kc)
; #pragma unroll
;             for (int db = 0; db < 4; ++db) {
;                 const LAS unsigned char* va = vrow + ((db ^ swz) << 5) + (32 * kc) * 128;
;                 const bf16x8 vf = cat8(vtr(va), vtr(va + 16 * 128));
; #pragma unroll
;                 for (int gi = 0; gi < GPB; ++gi) O[GPB * gh + gi][db] = __builtin_amdgcn_mfma_f32_16x16x32_bf16(vf, pf[gi][kc], O[GPB * gh + gi][db], 0, 0, 0);
;             }
; __device__ __forceinline__ void swa_phase(LAS unsigned char* lds, const bf16_t* Q, const bf16_t* K, const bf16_t* V, bf16_t* Ob, const float* sink, float negb) {
;     ...
;             ring_wait<2>();
;         }
;         for (int t = 4; t < NT; ++t) {
;             dma_tile<1>(lds + ((t + 3) & 3) * SW_BUF, K, V, SW_ROW0(t + 3), 256, dl, w);
;             const LAS unsigned char* buf = lds + (t & 3) * SW_BUF;
;             const int start = 128 * tb - 128 + 64 * (i_lo + t - 4);
;             if (start + 63 >= tq - 128 && start <= tq + 15 + 128)
;                 full_tile<1, 2, 2>(O, ls, qf, negb, buf, buf + 8192, lane, start - (tq + l15));
	v_mfma_f32_16x16x32_bf16 v[104:107], v[160:163], v[4:7], v[0:3]
	v_mfma_f32_16x16x32_bf16 v[108:111], v[168:171], v[4:7], v[0:3]
	v_mfma_f32_16x16x32_bf16 v[112:115], v[160:163], v[8:11], v[0:3]
	v_mfma_f32_16x16x32_bf16 v[116:119], v[168:171], v[8:11], v[0:3]
	v_mfma_f32_16x16x32_bf16 v[136:139], v[160:163], v[20:23], v[0:3]
	v_mfma_f32_16x16x32_bf16 v[140:143], v[168:171], v[20:23], v[0:3]
	v_mfma_f32_16x16x32_bf16 v[176:179], v[160:163], v[28:31], v[0:3]
	v_mfma_f32_16x16x32_bf16 v[232:235], v[168:171], v[28:31], v[0:3]
	v_mfma_f32_16x16x32_bf16 v[104:107], v[164:167], v[12:15], v[104:107]
	v_mfma_f32_16x16x32_bf16 v[108:111], v[172:175], v[12:15], v[108:111]
	v_mfma_f32_16x16x32_bf16 v[112:115], v[164:167], v[16:19], v[112:115]
	v_mfma_f32_16x16x32_bf16 v[116:119], v[172:175], v[16:19], v[116:119]
	v_mfma_f32_16x16x32_bf16 v[136:139], v[164:167], v[24:27], v[136:139]
	v_mfma_f32_16x16x32_bf16 v[140:143], v[172:175], v[24:27], v[140:143]
	v_mfma_f32_16x16x32_bf16 v[176:179], v[164:167], v[32:35], v[176:179]
	v_mfma_f32_16x16x32_bf16 v[232:235], v[172:175], v[32:35], v[232:235]
	ds_read_b64_tr_b16 v[216:217], v103 offset:12288
	ds_read_b64_tr_b16 v[218:219], v103 offset:14336
	ds_read_b64_tr_b16 v[220:221], v133 offset:12288
	ds_read_b64_tr_b16 v[222:223], v133 offset:14336
	ds_read_b64_tr_b16 v[224:225], v134 offset:12288
	ds_read_b64_tr_b16 v[226:227], v134 offset:14336
	ds_read_b64_tr_b16 v[228:229], v135 offset:12288
	ds_read_b64_tr_b16 v[230:231], v135 offset:14336
	v_exp_f32_e32 v104, v104
	v_exp_f32_e32 v105, v105
	v_exp_f32_e32 v106, v106
	v_add_f32_e32 v144, v104, v105
	v_exp_f32_e32 v107, v107
	v_exp_f32_e32 v108, v108
	v_add_f32_e32 v144, v144, v106
	v_exp_f32_e32 v109, v109
	v_add_f32_e32 v144, v144, v107
	v_exp_f32_e32 v110, v110
	v_add_f32_e32 v144, v144, v108
	v_exp_f32_e32 v111, v111
	v_add_f32_e32 v144, v144, v109
	v_cvt_pk_bf16_f32 v104, v104, v105
	v_add_f32_e32 v144, v144, v110
	v_cvt_pk_bf16_f32 v105, v106, v107
	v_cvt_pk_bf16_f32 v106, v108, v109
	v_cvt_pk_bf16_f32 v107, v110, v111
	v_add_f32_e32 v144, v144, v111
	v_add_f32_e32 v131, v131, v144
	v_exp_f32_e32 v112, v112
	v_exp_f32_e32 v113, v113
	v_exp_f32_e32 v114, v114
	v_add_f32_e32 v144, v112, v113
	v_exp_f32_e32 v115, v115
	v_exp_f32_e32 v116, v116
	v_add_f32_e32 v144, v144, v114
	v_exp_f32_e32 v117, v117
	v_add_f32_e32 v144, v144, v115
	v_exp_f32_e32 v118, v118
	v_add_f32_e32 v144, v144, v116
	v_exp_f32_e32 v119, v119
	v_add_f32_e32 v144, v144, v117
	v_cvt_pk_bf16_f32 v112, v112, v113
	v_add_f32_e32 v144, v144, v118
	v_cvt_pk_bf16_f32 v113, v114, v115
	v_cvt_pk_bf16_f32 v114, v116, v117
	v_cvt_pk_bf16_f32 v115, v118, v119
	v_add_f32_e32 v144, v144, v119
	v_add_f32_e32 v130, v130, v144
	v_exp_f32_e32 v136, v136
	v_exp_f32_e32 v137, v137
	v_exp_f32_e32 v138, v138
	v_add_f32_e32 v144, v136, v137
	v_exp_f32_e32 v139, v139
	v_exp_f32_e32 v140, v140
	v_add_f32_e32 v144, v144, v138
	v_exp_f32_e32 v141, v141
	v_add_f32_e32 v144, v144, v139
	v_exp_f32_e32 v142, v142
	v_add_f32_e32 v144, v144, v140
	v_exp_f32_e32 v143, v143
	v_add_f32_e32 v144, v144, v141
	v_cvt_pk_bf16_f32 v136, v136, v137
	v_add_f32_e32 v144, v144, v142
	v_cvt_pk_bf16_f32 v137, v138, v139
	v_cvt_pk_bf16_f32 v138, v140, v141
	v_cvt_pk_bf16_f32 v139, v142, v143
	v_add_f32_e32 v144, v144, v143
	v_add_f32_e32 v129, v129, v144
	v_exp_f32_e32 v176, v176
	v_exp_f32_e32 v177, v177
	v_exp_f32_e32 v178, v178
	v_add_f32_e32 v144, v176, v177
	v_exp_f32_e32 v179, v179
	v_exp_f32_e32 v232, v232
	v_add_f32_e32 v144, v144, v178
	v_exp_f32_e32 v233, v233
	v_add_f32_e32 v144, v144, v179
	v_exp_f32_e32 v234, v234
	v_add_f32_e32 v144, v144, v232
	v_exp_f32_e32 v235, v235
	v_add_f32_e32 v144, v144, v233
	v_cvt_pk_bf16_f32 v176, v176, v177
	v_add_f32_e32 v144, v144, v234
	v_cvt_pk_bf16_f32 v177, v178, v179
	v_cvt_pk_bf16_f32 v178, v232, v233
	v_cvt_pk_bf16_f32 v179, v234, v235
	v_add_f32_e32 v144, v144, v235
	v_add_f32_e32 v128, v128, v144
	s_waitcnt lgkmcnt(0)
	v_mfma_f32_16x16x32_bf16 v[64:67], v[216:219], v[104:107], v[64:67]
	v_mfma_f32_16x16x32_bf16 v[60:63], v[220:223], v[104:107], v[60:63]
	v_mfma_f32_16x16x32_bf16 v[56:59], v[224:227], v[104:107], v[56:59]
	v_mfma_f32_16x16x32_bf16 v[52:55], v[228:231], v[104:107], v[52:55]
	v_mfma_f32_16x16x32_bf16 v[48:51], v[216:219], v[112:115], v[48:51]
	v_mfma_f32_16x16x32_bf16 v[44:47], v[220:223], v[112:115], v[44:47]
	v_mfma_f32_16x16x32_bf16 v[40:43], v[224:227], v[112:115], v[40:43]
	v_mfma_f32_16x16x32_bf16 v[36:39], v[228:231], v[112:115], v[36:39]
	v_mfma_f32_16x16x32_bf16 v[72:75], v[216:219], v[136:139], v[72:75]
	v_mfma_f32_16x16x32_bf16 v[84:87], v[220:223], v[136:139], v[84:87]
	v_mfma_f32_16x16x32_bf16 v[88:91], v[224:227], v[136:139], v[88:91]
	v_mfma_f32_16x16x32_bf16 v[96:99], v[228:231], v[136:139], v[96:99]
	v_mfma_f32_16x16x32_bf16 v[68:71], v[216:219], v[176:179], v[68:71]
	v_mfma_f32_16x16x32_bf16 v[76:79], v[220:223], v[176:179], v[76:79]
	v_mfma_f32_16x16x32_bf16 v[80:83], v[224:227], v[176:179], v[80:83]
	v_mfma_f32_16x16x32_bf16 v[92:95], v[228:231], v[176:179], v[92:95]
	s_addk_i32 s1, 0x4000
	s_add_u32 s7, s7, 64
	s_addc_u32 s8, s8, 0
	s_add_i32 s6, s6, 1
	s_waitcnt vmcnt(4)
	s_barrier
	s_add_i32 s48, s0, 0xffffff80
	s_add_i32 s49, s0, 0x8f
	s_add_i32 s50, s45, 0xffffffbf
	s_mov_b32 s51, 0
	s_mov_b32 s52, 0x10000
	v_mov_b32_e32 v132, v211
	s_branch .LBB0_355

; #define LAS __attribute__((address_space(3)))
;     ...
; #pragma unroll
;     for (int gh = 0; gh < 4 / GPB; ++gh) {
;         f32x4 S[GPB][4];
; #pragma unroll
;         for (int kb = 0; kb < 4; ++kb) {
;             const bf16x8 kf0 = *(const LAS bf16x8*)(kb0 + (16 * kb) * 128 + kx0), kf1 = *(const LAS bf16x8*)(kb0 + (16 * kb) * 128 + kx1);
; #pragma unroll
;             for (int gi = 0; gi < GPB; ++gi) { S[gi][kb] = __builtin_amdgcn_mfma_f32_16x16x32_bf16(kf0, qf[GPB * gh + gi][0], cinit, 0, 0, 0);
;                 S[gi][kb] = __builtin_amdgcn_mfma_f32_16x16x32_bf16(kf1, qf[GPB * gh + gi][1], S[gi][kb], 0, 0, 0); } }
;         bf16x8 pf[GPB][2];
; #pragma unroll
;         for (int gi = 0; gi < GPB; ++gi) {
;             if (MASK) {
; #pragma unroll
;                 for (int kb = 0; kb < 4; ++kb)
; #pragma unroll
;                     for (int i = 0; i < 4; ++i) { const int rel = rel0 + 16 * kb + 4 * g + i; S[gi][kb][i] = ((unsigned)(rel + 128) > 256u) ? NEGBIG : S[gi][kb][i]; }
; __device__ __forceinline__ void swa_phase(LAS unsigned char* lds, const bf16_t* Q, const bf16_t* K, const bf16_t* V, bf16_t* Ob, const float* sink, float negb) {
;     ...
;         for (int t = 4; t < NT; ++t) {
;             dma_tile<1>(lds + ((t + 3) & 3) * SW_BUF, K, V, SW_ROW0(t + 3), 256, dl, w);
;             const LAS unsigned char* buf = lds + (t & 3) * SW_BUF;
;             const int start = 128 * tb - 128 + 64 * (i_lo + t - 4);
;             if (start + 63 >= tq - 128 && start <= tq + 15 + 128)
;                 full_tile<1, 2, 2>(O, ls, qf, negb, buf, buf + 8192, lane, start - (tq + l15));
.LBB0_355:
	s_add_i32 s1, s52, 0xc000
	s_and_b32 s1, s1, 0xc000
	s_add_i32 s9, s47, s45
	s_add_i32 s8, s1, 0
	s_add_i32 s1, s9, 64
	s_add_i32 s0, s51, 7
	s_ashr_i32 s6, s1, 31
	s_add_u32 s7, s1, s43
	s_addc_u32 s1, s6, 0
	s_cmp_lt_u32 s0, s46
	s_cselect_b32 s1, s1, 0
	s_cselect_b32 s0, s7, s82
	s_lshl_b64 s[0:1], s[0:1], 9
	s_add_u32 s6, s67, s0
	s_addc_u32 s7, s4, s1
	s_add_u32 s0, s5, s0
	s_addc_u32 s1, s58, s1
	s_add_i32 s8, s38, s8
	s_mov_b32 s11, m0
	s_mov_b32 m0, s8
	s_nop 0
	global_load_lds_dwordx4 v212, s[6:7]
	s_mov_b32 m0, s11
	s_add_i32 s10, s8, 0x2000
	s_mov_b32 s6, m0
	s_mov_b32 m0, s10
	s_nop 0
	global_load_lds_dwordx4 v213, s[0:1]
	s_mov_b32 m0, s6
	s_addk_i32 s9, 0xff80
	s_add_i32 s0, s47, s50
	s_cmp_lt_i32 s0, s48
	s_cselect_b64 s[0:1], -1, 0
	s_cmp_gt_i32 s9, s49
	s_cselect_b64 s[6:7], -1, 0
	s_or_b64 s[0:1], s[0:1], s[6:7]
	s_and_b64 vcc, exec, s[0:1]
	s_cbranch_vccnz .LBB0_354
	s_and_b32 s34, s52, 0xc000
	v_add_u32_e32 v145, s47, v132
	s_movk_i32 s20, 0x100
	v_readfirstlane_b32 s30, v145
	s_nop 0
	s_sub_i32 s30, s30, 15
	s_cmp_le_u32 s30, 0xb2
	s_cbranch_scc1 .Lswa_loc_nomask
	v_add_u32_e32 v100, s34, v191
	v_add3_u32 v135, s34, v203, v198
	v_add_u32_e32 v102, v100, v193
	v_add_u32_e32 v100, v100, v192
	ds_read_b128 v[160:163], v100
	ds_read_b128 v[164:167], v102
	ds_read_b128 v[168:171], v100 offset:2048
	ds_read_b128 v[172:175], v102 offset:2048
	v_add_u32_e32 v103, v135, v199
	v_add_u32_e32 v133, v135, v200
	v_add_u32_e32 v134, v135, v201
	v_add_u32_e32 v135, v135, v202
	v_add_u32_e32 v216, 0, v145
	v_add_u32_e32 v217, 1, v145
	v_add_u32_e32 v218, 2, v145
	v_add_u32_e32 v219, 3, v145
	v_add_u32_e32 v220, 16, v145
	v_add_u32_e32 v221, 17, v145
	v_add_u32_e32 v222, 18, v145
	v_add_u32_e32 v223, 19, v145
	v_cmp_gt_u32_e64 s[0:1], v216, s20
	v_cmp_gt_u32_e64 s[6:7], v217, s20
	v_cmp_gt_u32_e64 s[8:9], v218, s20
	v_cmp_gt_u32_e64 s[10:11], v219, s20
	v_cmp_gt_u32_e64 s[12:13], v220, s20
	v_cmp_gt_u32_e64 s[24:25], v221, s20
	v_cmp_gt_u32_e64 s[26:27], v222, s20
	v_cmp_gt_u32_e64 s[28:29], v223, s20
	v_cndmask_b32_e64 v180, v0, v197, s[0:1]
	v_cndmask_b32_e64 v181, v0, v197, s[6:7]
	v_cndmask_b32_e64 v182, v0, v197, s[8:9]
	v_cndmask_b32_e64 v183, v0, v197, s[10:11]
	v_cndmask_b32_e64 v236, v0, v197, s[12:13]
	v_cndmask_b32_e64 v237, v0, v197, s[24:25]
	v_cndmask_b32_e64 v238, v0, v197, s[26:27]
	v_cndmask_b32_e64 v239, v0, v197, s[28:29]
	s_waitcnt lgkmcnt(0)
	v_mfma_f32_16x16x32_bf16 v[104:107], v[160:163], v[4:7], v[180:183]
	v_mfma_f32_16x16x32_bf16 v[108:111], v[168:171], v[4:7], v[236:239]
	v_mfma_f32_16x16x32_bf16 v[112:115], v[160:163], v[8:11], v[180:183]
	v_mfma_f32_16x16x32_bf16 v[116:119], v[168:171], v[8:11], v[236:239]
	v_mfma_f32_16x16x32_bf16 v[136:139], v[160:163], v[20:23], v[180:183]
	v_mfma_f32_16x16x32_bf16 v[140:143], v[168:171], v[20:23], v[236:239]
	v_mfma_f32_16x16x32_bf16 v[176:179], v[160:163], v[28:31], v[180:183]
	v_mfma_f32_16x16x32_bf16 v[232:235], v[168:171], v[28:31], v[236:239]
	v_mfma_f32_16x16x32_bf16 v[104:107], v[164:167], v[12:15], v[104:107]
	v_mfma_f32_16x16x32_bf16 v[108:111], v[172:175], v[12:15], v[108:111]
	v_mfma_f32_16x16x32_bf16 v[112:115], v[164:167], v[16:19], v[112:115]
	v_mfma_f32_16x16x32_bf16 v[116:119], v[172:175], v[16:19], v[116:119]
	v_mfma_f32_16x16x32_bf16 v[136:139], v[164:167], v[24:27], v[136:139]
	v_mfma_f32_16x16x32_bf16 v[140:143], v[172:175], v[24:27], v[140:143]
	v_mfma_f32_16x16x32_bf16 v[176:179], v[164:167], v[32:35], v[176:179]
	v_mfma_f32_16x16x32_bf16 v[232:235], v[172:175], v[32:35], v[232:235]
	v_add_u32_e32 v216, 32, v145
	v_add_u32_e32 v217, 33, v145
	v_add_u32_e32 v218, 34, v145
	v_add_u32_e32 v219, 35, v145
	v_add_u32_e32 v220, 48, v145
	v_add_u32_e32 v221, 49, v145
	v_add_u32_e32 v222, 50, v145
	v_add_u32_e32 v223, 51, v145
	v_cmp_gt_u32_e64 s[0:1], v216, s20
	v_cmp_gt_u32_e64 s[6:7], v217, s20
	v_cmp_gt_u32_e64 s[8:9], v218, s20
	v_cmp_gt_u32_e64 s[10:11], v219, s20
	v_cmp_gt_u32_e64 s[12:13], v220, s20
	v_cmp_gt_u32_e64 s[24:25], v221, s20
	v_cmp_gt_u32_e64 s[26:27], v222, s20
	v_cmp_gt_u32_e64 s[28:29], v223, s20
	v_cndmask_b32_e64 v180, v0, v197, s[0:1]
	v_cndmask_b32_e64 v181, v0, v197, s[6:7]
	v_cndmask_b32_e64 v182, v0, v197, s[8:9]
	v_cndmask_b32_e64 v183, v0, v197, s[10:11]
	v_cndmask_b32_e64 v236, v0, v197, s[12:13]
	v_cndmask_b32_e64 v237, v0, v197, s[24:25]
	v_cndmask_b32_e64 v238, v0, v197, s[26:27]
	v_cndmask_b32_e64 v239, v0, v197, s[28:29]
	ds_read_b64_tr_b16 v[216:217], v103 offset:8192
	ds_read_b64_tr_b16 v[218:219], v103 offset:10240
	ds_read_b64_tr_b16 v[220:221], v133 offset:8192
	ds_read_b64_tr_b16 v[222:223], v133 offset:10240
	ds_read_b64_tr_b16 v[224:225], v134 offset:8192
	ds_read_b64_tr_b16 v[226:227], v134 offset:10240
	ds_read_b64_tr_b16 v[228:229], v135 offset:8192
	ds_read_b64_tr_b16 v[230:231], v135 offset:10240
	ds_read_b128 v[160:163], v100 offset:4096
	ds_read_b128 v[164:167], v102 offset:4096
	ds_read_b128 v[168:171], v100 offset:6144
	ds_read_b128 v[172:175], v102 offset:6144
	v_exp_f32_e32 v104, v104
	v_exp_f32_e32 v105, v105
	v_exp_f32_e32 v106, v106
	v_add_f32_e32 v144, v104, v105
	v_exp_f32_e32 v107, v107
	v_exp_f32_e32 v108, v108
	v_add_f32_e32 v144, v144, v106
	v_exp_f32_e32 v109, v109
	v_add_f32_e32 v144, v144, v107
	v_exp_f32_e32 v110, v110
	v_add_f32_e32 v144, v144, v108
	v_exp_f32_e32 v111, v111
	v_add_f32_e32 v144, v144, v109
	v_cvt_pk_bf16_f32 v104, v104, v105
	v_add_f32_e32 v144, v144, v110
	v_cvt_pk_bf16_f32 v105, v106, v107
	v_cvt_pk_bf16_f32 v106, v108, v109
	v_cvt_pk_bf16_f32 v107, v110, v111
	v_add_f32_e32 v144, v144, v111
	v_add_f32_e32 v131, v131, v144
	v_exp_f32_e32 v112, v112
; #define LAS __attribute__((address_space(3)))
; __device__ __forceinline__ s16x4 vtr(const LAS unsigned char* p) { return __builtin_bit_cast(s16x4, __builtin_amdgcn_ds_read_tr16_b64_v4i16((LAS v4i16_t*)p)); }
; __device__ __forceinline__ bf16x8 cat8(s16x4 a, s16x4 b) { return (bf16x8){a[0], a[1], a[2], a[3], b[0], b[1], b[2], b[3]}; }
;     ...
; #pragma unroll
;     for (int gh = 0; gh < 4 / GPB; ++gh) {
;         f32x4 S[GPB][4];
; #pragma unroll
;         for (int kb = 0; kb < 4; ++kb) {
;             const bf16x8 kf0 = *(const LAS bf16x8*)(kb0 + (16 * kb) * 128 + kx0), kf1 = *(const LAS bf16x8*)(kb0 + (16 * kb) * 128 + kx1);
; #pragma unroll
;             for (int gi = 0; gi < GPB; ++gi) { S[gi][kb] = __builtin_amdgcn_mfma_f32_16x16x32_bf16(kf0, qf[GPB * gh + gi][0], cinit, 0, 0, 0);
;                 S[gi][kb] = __builtin_amdgcn_mfma_f32_16x16x32_bf16(kf1, qf[GPB * gh + gi][1], S[gi][kb], 0, 0, 0); } }
;         bf16x8 pf[GPB][2];
; #pragma unroll
;         for (int gi = 0; gi < GPB; ++gi) {
;             if (MASK) {
; #pragma unroll
;                 for (int kb = 0; kb < 4; ++kb)
; #pragma unroll
;                     for (int i = 0; i < 4; ++i) { const int rel = rel0 + 16 * kb + 4 * g + i; S[gi][kb][i] = ((unsigned)(rel + 128) > 256u) ? NEGBIG : S[gi][kb][i]; }
;             }
;             ls[GPB * gh + gi] += exp_step<4>(S[gi]);
;             pf[gi][0] = pack8(S[gi][0], S[gi][1]); pf[gi][1] = pack8(S[gi][2], S[gi][3]);
;         }
; #pragma unroll
;         for (int kc = 0; kc < 2; ++kc)
; #pragma unroll
;             for (int db = 0; db < 4; ++db) {
;                 const LAS unsigned char* va = vrow + ((db ^ swz) << 5) + (32 * kc) * 128;
;                 const bf16x8 vf = cat8(vtr(va), vtr(va + 16 * 128));
; #pragma unroll
;                 for (int gi = 0; gi < GPB; ++gi) O[GPB * gh + gi][db] = __builtin_amdgcn_mfma_f32_16x16x32_bf16(vf, pf[gi][kc], O[GPB * gh + gi][db], 0, 0, 0);
;             }
; __device__ __forceinline__ void swa_phase(LAS unsigned char* lds, const bf16_t* Q, const bf16_t* K, const bf16_t* V, bf16_t* Ob, const float* sink, float negb) {
;     ...
;             if (start + 63 >= tq - 128 && start <= tq + 15 + 128)
;                 full_tile<1, 2, 2>(O, ls, qf, negb, buf, buf + 8192, lane, start - (tq + l15));
	v_exp_f32_e32 v113, v113
	v_exp_f32_e32 v114, v114
	v_add_f32_e32 v144, v112, v113
	v_exp_f32_e32 v115, v115
	v_exp_f32_e32 v116, v116
	v_add_f32_e32 v144, v144, v114
	v_exp_f32_e32 v117, v117
	v_add_f32_e32 v144, v144, v115
	v_exp_f32_e32 v118, v118
	v_add_f32_e32 v144, v144, v116
	v_exp_f32_e32 v119, v119
	v_add_f32_e32 v144, v144, v117
	v_cvt_pk_bf16_f32 v112, v112, v113
	v_add_f32_e32 v144, v144, v118
	v_cvt_pk_bf16_f32 v113, v114, v115
	v_cvt_pk_bf16_f32 v114, v116, v117
	v_cvt_pk_bf16_f32 v115, v118, v119
	v_add_f32_e32 v144, v144, v119
	v_add_f32_e32 v130, v130, v144
	v_exp_f32_e32 v136, v136
	v_exp_f32_e32 v137, v137
	v_exp_f32_e32 v138, v138
	v_add_f32_e32 v144, v136, v137
	v_exp_f32_e32 v139, v139
	v_exp_f32_e32 v140, v140
	v_add_f32_e32 v144, v144, v138
	v_exp_f32_e32 v141, v141
	v_add_f32_e32 v144, v144, v139
	v_exp_f32_e32 v142, v142
	v_add_f32_e32 v144, v144, v140
	v_exp_f32_e32 v143, v143
	v_add_f32_e32 v144, v144, v141
	v_cvt_pk_bf16_f32 v136, v136, v137
	v_add_f32_e32 v144, v144, v142
	v_cvt_pk_bf16_f32 v137, v138, v139
	v_cvt_pk_bf16_f32 v138, v140, v141
	v_cvt_pk_bf16_f32 v139, v142, v143
	v_add_f32_e32 v144, v144, v143
	v_add_f32_e32 v129, v129, v144
	v_exp_f32_e32 v176, v176
	v_exp_f32_e32 v177, v177
	v_exp_f32_e32 v178, v178
	v_add_f32_e32 v144, v176, v177
	v_exp_f32_e32 v179, v179
	v_exp_f32_e32 v232, v232
	v_add_f32_e32 v144, v144, v178
	v_exp_f32_e32 v233, v233
	v_add_f32_e32 v144, v144, v179
	v_exp_f32_e32 v234, v234
	v_add_f32_e32 v144, v144, v232
	v_exp_f32_e32 v235, v235
	v_add_f32_e32 v144, v144, v233
	v_cvt_pk_bf16_f32 v176, v176, v177
	v_add_f32_e32 v144, v144, v234
	v_cvt_pk_bf16_f32 v177, v178, v179
	v_cvt_pk_bf16_f32 v178, v232, v233
	v_cvt_pk_bf16_f32 v179, v234, v235
	v_add_f32_e32 v144, v144, v235
	v_add_f32_e32 v128, v128, v144
	s_waitcnt lgkmcnt(4)
	v_mfma_f32_16x16x32_bf16 v[64:67], v[216:219], v[104:107], v[64:67]
	v_mfma_f32_16x16x32_bf16 v[60:63], v[220:223], v[104:107], v[60:63]
	v_mfma_f32_16x16x32_bf16 v[56:59], v[224:227], v[104:107], v[56:59]
	v_mfma_f32_16x16x32_bf16 v[52:55], v[228:231], v[104:107], v[52:55]
	v_mfma_f32_16x16x32_bf16 v[48:51], v[216:219], v[112:115], v[48:51]
	v_mfma_f32_16x16x32_bf16 v[44:47], v[220:223], v[112:115], v[44:47]
	v_mfma_f32_16x16x32_bf16 v[40:43], v[224:227], v[112:115], v[40:43]
	v_mfma_f32_16x16x32_bf16 v[36:39], v[228:231], v[112:115], v[36:39]
	v_mfma_f32_16x16x32_bf16 v[72:75], v[216:219], v[136:139], v[72:75]
	v_mfma_f32_16x16x32_bf16 v[84:87], v[220:223], v[136:139], v[84:87]
	v_mfma_f32_16x16x32_bf16 v[88:91], v[224:227], v[136:139], v[88:91]
	v_mfma_f32_16x16x32_bf16 v[96:99], v[228:231], v[136:139], v[96:99]
	v_mfma_f32_16x16x32_bf16 v[68:71], v[216:219], v[176:179], v[68:71]
	v_mfma_f32_16x16x32_bf16 v[76:79], v[220:223], v[176:179], v[76:79]
	v_mfma_f32_16x16x32_bf16 v[80:83], v[224:227], v[176:179], v[80:83]
	v_mfma_f32_16x16x32_bf16 v[92:95], v[228:231], v[176:179], v[92:95]
	s_waitcnt lgkmcnt(0)
	v_mfma_f32_16x16x32_bf16 v[104:107], v[160:163], v[4:7], v[180:183]
	v_mfma_f32_16x16x32_bf16 v[108:111], v[168:171], v[4:7], v[236:239]
	v_mfma_f32_16x16x32_bf16 v[112:115], v[160:163], v[8:11], v[180:183]
	v_mfma_f32_16x16x32_bf16 v[116:119], v[168:171], v[8:11], v[236:239]
	v_mfma_f32_16x16x32_bf16 v[136:139], v[160:163], v[20:23], v[180:183]
	v_mfma_f32_16x16x32_bf16 v[140:143], v[168:171], v[20:23], v[236:239]
	v_mfma_f32_16x16x32_bf16 v[176:179], v[160:163], v[28:31], v[180:183]
	v_mfma_f32_16x16x32_bf16 v[232:235], v[168:171], v[28:31], v[236:239]
	v_mfma_f32_16x16x32_bf16 v[104:107], v[164:167], v[12:15], v[104:107]
	v_mfma_f32_16x16x32_bf16 v[108:111], v[172:175], v[12:15], v[108:111]
	v_mfma_f32_16x16x32_bf16 v[112:115], v[164:167], v[16:19], v[112:115]
	v_mfma_f32_16x16x32_bf16 v[116:119], v[172:175], v[16:19], v[116:119]
	v_mfma_f32_16x16x32_bf16 v[136:139], v[164:167], v[24:27], v[136:139]
	v_mfma_f32_16x16x32_bf16 v[140:143], v[172:175], v[24:27], v[140:143]
	v_mfma_f32_16x16x32_bf16 v[176:179], v[164:167], v[32:35], v[176:179]
	v_mfma_f32_16x16x32_bf16 v[232:235], v[172:175], v[32:35], v[232:235]
	ds_read_b64_tr_b16 v[216:217], v103 offset:12288
	ds_read_b64_tr_b16 v[218:219], v103 offset:14336
	ds_read_b64_tr_b16 v[220:221], v133 offset:12288
	ds_read_b64_tr_b16 v[222:223], v133 offset:14336
	ds_read_b64_tr_b16 v[224:225], v134 offset:12288
	ds_read_b64_tr_b16 v[226:227], v134 offset:14336
	ds_read_b64_tr_b16 v[228:229], v135 offset:12288
	ds_read_b64_tr_b16 v[230:231], v135 offset:14336
	v_exp_f32_e32 v104, v104
	v_exp_f32_e32 v105, v105
	v_exp_f32_e32 v106, v106
	v_add_f32_e32 v144, v104, v105
	v_exp_f32_e32 v107, v107
	v_exp_f32_e32 v108, v108
	v_add_f32_e32 v144, v144, v106
	v_exp_f32_e32 v109, v109
	v_add_f32_e32 v144, v144, v107
	v_exp_f32_e32 v110, v110
	v_add_f32_e32 v144, v144, v108
	v_exp_f32_e32 v111, v111
	v_add_f32_e32 v144, v144, v109
	v_cvt_pk_bf16_f32 v104, v104, v105
	v_add_f32_e32 v144, v144, v110
	v_cvt_pk_bf16_f32 v105, v106, v107
	v_cvt_pk_bf16_f32 v106, v108, v109
	v_cvt_pk_bf16_f32 v107, v110, v111
	v_add_f32_e32 v144, v144, v111
	v_add_f32_e32 v131, v131, v144
	v_exp_f32_e32 v112, v112
	v_exp_f32_e32 v113, v113
	v_exp_f32_e32 v114, v114
	v_add_f32_e32 v144, v112, v113
	v_exp_f32_e32 v115, v115
	v_exp_f32_e32 v116, v116
	v_add_f32_e32 v144, v144, v114
	v_exp_f32_e32 v117, v117
	v_add_f32_e32 v144, v144, v115
	v_exp_f32_e32 v118, v118
	v_add_f32_e32 v144, v144, v116
	v_exp_f32_e32 v119, v119
	v_add_f32_e32 v144, v144, v117
	v_cvt_pk_bf16_f32 v112, v112, v113
	v_add_f32_e32 v144, v144, v118
	v_cvt_pk_bf16_f32 v113, v114, v115
	v_cvt_pk_bf16_f32 v114, v116, v117
	v_cvt_pk_bf16_f32 v115, v118, v119
	v_add_f32_e32 v144, v144, v119
	v_add_f32_e32 v130, v130, v144
	v_exp_f32_e32 v136, v136
	v_exp_f32_e32 v137, v137
	v_exp_f32_e32 v138, v138
	v_add_f32_e32 v144, v136, v137
	v_exp_f32_e32 v139, v139
	v_exp_f32_e32 v140, v140
	v_add_f32_e32 v144, v144, v138
	v_exp_f32_e32 v141, v141
	v_add_f32_e32 v144, v144, v139
	v_exp_f32_e32 v142, v142
	v_add_f32_e32 v144, v144, v140
	v_exp_f32_e32 v143, v143
	v_add_f32_e32 v144, v144, v141
	v_cvt_pk_bf16_f32 v136, v136, v137
	v_add_f32_e32 v144, v144, v142
	v_cvt_pk_bf16_f32 v137, v138, v139
	v_cvt_pk_bf16_f32 v138, v140, v141
	v_cvt_pk_bf16_f32 v139, v142, v143
	v_add_f32_e32 v144, v144, v143
	v_add_f32_e32 v129, v129, v144
	v_exp_f32_e32 v176, v176
	v_exp_f32_e32 v177, v177
	v_exp_f32_e32 v178, v178
	v_add_f32_e32 v144, v176, v177
	v_exp_f32_e32 v179, v179
	v_exp_f32_e32 v232, v232
	v_add_f32_e32 v144, v144, v178
	v_exp_f32_e32 v233, v233
	v_add_f32_e32 v144, v144, v179
	v_exp_f32_e32 v234, v234
	v_add_f32_e32 v144, v144, v232
	v_exp_f32_e32 v235, v235
	v_add_f32_e32 v144, v144, v233
	v_cvt_pk_bf16_f32 v176, v176, v177
	v_add_f32_e32 v144, v144, v234
	v_cvt_pk_bf16_f32 v177, v178, v179
	v_cvt_pk_bf16_f32 v178, v232, v233
	v_cvt_pk_bf16_f32 v179, v234, v235
	v_add_f32_e32 v144, v144, v235
	v_add_f32_e32 v128, v128, v144
	s_waitcnt lgkmcnt(0)
; #define LAS __attribute__((address_space(3)))
; __device__ __forceinline__ s16x4 vtr(const LAS unsigned char* p) { return __builtin_bit_cast(s16x4, __builtin_amdgcn_ds_read_tr16_b64_v4i16((LAS v4i16_t*)p)); }
; __device__ __forceinline__ bf16x8 cat8(s16x4 a, s16x4 b) { return (bf16x8){a[0], a[1], a[2], a[3], b[0], b[1], b[2], b[3]}; }
;     ...
; #pragma unroll
;     for (int gh = 0; gh < 4 / GPB; ++gh) {
;         f32x4 S[GPB][4];
; #pragma unroll
;         for (int kb = 0; kb < 4; ++kb) {
;             const bf16x8 kf0 = *(const LAS bf16x8*)(kb0 + (16 * kb) * 128 + kx0), kf1 = *(const LAS bf16x8*)(kb0 + (16 * kb) * 128 + kx1);
; #pragma unroll
;             for (int gi = 0; gi < GPB; ++gi) { S[gi][kb] = __builtin_amdgcn_mfma_f32_16x16x32_bf16(kf0, qf[GPB * gh + gi][0], cinit, 0, 0, 0);
;                 S[gi][kb] = __builtin_amdgcn_mfma_f32_16x16x32_bf16(kf1, qf[GPB * gh + gi][1], S[gi][kb], 0, 0, 0); } }
;         bf16x8 pf[GPB][2];
; #pragma unroll
;         for (int gi = 0; gi < GPB; ++gi) {
;             if (MASK) {
; #pragma unroll
;                 for (int kb = 0; kb < 4; ++kb)
; #pragma unroll
;                     for (int i = 0; i < 4; ++i) { const int rel = rel0 + 16 * kb + 4 * g + i; S[gi][kb][i] = ((unsigned)(rel + 128) > 256u) ? NEGBIG : S[gi][kb][i]; }
;             }
;             ls[GPB * gh + gi] += exp_step<4>(S[gi]);
;             pf[gi][0] = pack8(S[gi][0], S[gi][1]); pf[gi][1] = pack8(S[gi][2], S[gi][3]);
;         }
; #pragma unroll
;         for (int kc = 0; kc < 2; ++kc)
; #pragma unroll
;             for (int db = 0; db < 4; ++db) {
;                 const LAS unsigned char* va = vrow + ((db ^ swz) << 5) + (32 * kc) * 128;
;                 const bf16x8 vf = cat8(vtr(va), vtr(va + 16 * 128));
; #pragma unroll
;                 for (int gi = 0; gi < GPB; ++gi) O[GPB * gh + gi][db] = __builtin_amdgcn_mfma_f32_16x16x32_bf16(vf, pf[gi][kc], O[GPB * gh + gi][db], 0, 0, 0);
;             }
; __device__ __forceinline__ void swa_phase(LAS unsigned char* lds, const bf16_t* Q, const bf16_t* K, const bf16_t* V, bf16_t* Ob, const float* sink, float negb) {
;     ...
;             if (start + 63 >= tq - 128 && start <= tq + 15 + 128)
;                 full_tile<1, 2, 2>(O, ls, qf, negb, buf, buf + 8192, lane, start - (tq + l15));
	v_mfma_f32_16x16x32_bf16 v[64:67], v[216:219], v[104:107], v[64:67]
	v_mfma_f32_16x16x32_bf16 v[60:63], v[220:223], v[104:107], v[60:63]
	v_mfma_f32_16x16x32_bf16 v[56:59], v[224:227], v[104:107], v[56:59]
	v_mfma_f32_16x16x32_bf16 v[52:55], v[228:231], v[104:107], v[52:55]
	v_mfma_f32_16x16x32_bf16 v[48:51], v[216:219], v[112:115], v[48:51]
	v_mfma_f32_16x16x32_bf16 v[44:47], v[220:223], v[112:115], v[44:47]
	v_mfma_f32_16x16x32_bf16 v[40:43], v[224:227], v[112:115], v[40:43]
	v_mfma_f32_16x16x32_bf16 v[36:39], v[228:231], v[112:115], v[36:39]
	v_mfma_f32_16x16x32_bf16 v[72:75], v[216:219], v[136:139], v[72:75]
	v_mfma_f32_16x16x32_bf16 v[84:87], v[220:223], v[136:139], v[84:87]
	v_mfma_f32_16x16x32_bf16 v[88:91], v[224:227], v[136:139], v[88:91]
	v_mfma_f32_16x16x32_bf16 v[96:99], v[228:231], v[136:139], v[96:99]
	v_mfma_f32_16x16x32_bf16 v[68:71], v[216:219], v[176:179], v[68:71]
	v_mfma_f32_16x16x32_bf16 v[76:79], v[220:223], v[176:179], v[76:79]
	v_mfma_f32_16x16x32_bf16 v[80:83], v[224:227], v[176:179], v[80:83]
	v_mfma_f32_16x16x32_bf16 v[92:95], v[228:231], v[176:179], v[92:95]
	s_branch .LBB0_354
.Lswa_loc_nomask:
	v_add_u32_e32 v100, s34, v191
	v_add3_u32 v135, s34, v203, v198
	v_add_u32_e32 v102, v100, v193
	v_add_u32_e32 v100, v100, v192
	ds_read_b128 v[160:163], v100
	ds_read_b128 v[164:167], v102
	ds_read_b128 v[168:171], v100 offset:2048
	ds_read_b128 v[172:175], v102 offset:2048
	v_add_u32_e32 v103, v135, v199
	v_add_u32_e32 v133, v135, v200
	v_add_u32_e32 v134, v135, v201
	v_add_u32_e32 v135, v135, v202
	s_waitcnt lgkmcnt(0)
	v_mfma_f32_16x16x32_bf16 v[104:107], v[160:163], v[4:7], v[0:3]
	v_mfma_f32_16x16x32_bf16 v[108:111], v[168:171], v[4:7], v[0:3]
	v_mfma_f32_16x16x32_bf16 v[112:115], v[160:163], v[8:11], v[0:3]
	v_mfma_f32_16x16x32_bf16 v[116:119], v[168:171], v[8:11], v[0:3]
	v_mfma_f32_16x16x32_bf16 v[136:139], v[160:163], v[20:23], v[0:3]
	v_mfma_f32_16x16x32_bf16 v[140:143], v[168:171], v[20:23], v[0:3]
	v_mfma_f32_16x16x32_bf16 v[176:179], v[160:163], v[28:31], v[0:3]
	v_mfma_f32_16x16x32_bf16 v[232:235], v[168:171], v[28:31], v[0:3]
	v_mfma_f32_16x16x32_bf16 v[104:107], v[164:167], v[12:15], v[104:107]
	v_mfma_f32_16x16x32_bf16 v[108:111], v[172:175], v[12:15], v[108:111]
	v_mfma_f32_16x16x32_bf16 v[112:115], v[164:167], v[16:19], v[112:115]
	v_mfma_f32_16x16x32_bf16 v[116:119], v[172:175], v[16:19], v[116:119]
	v_mfma_f32_16x16x32_bf16 v[136:139], v[164:167], v[24:27], v[136:139]
	v_mfma_f32_16x16x32_bf16 v[140:143], v[172:175], v[24:27], v[140:143]
	v_mfma_f32_16x16x32_bf16 v[176:179], v[164:167], v[32:35], v[176:179]
	v_mfma_f32_16x16x32_bf16 v[232:235], v[172:175], v[32:35], v[232:235]
	ds_read_b64_tr_b16 v[216:217], v103 offset:8192
	ds_read_b64_tr_b16 v[218:219], v103 offset:10240
	ds_read_b64_tr_b16 v[220:221], v133 offset:8192
	ds_read_b64_tr_b16 v[222:223], v133 offset:10240
	ds_read_b64_tr_b16 v[224:225], v134 offset:8192
	ds_read_b64_tr_b16 v[226:227], v134 offset:10240
	ds_read_b64_tr_b16 v[228:229], v135 offset:8192
	ds_read_b64_tr_b16 v[230:231], v135 offset:10240
	ds_read_b128 v[160:163], v100 offset:4096
	ds_read_b128 v[164:167], v102 offset:4096
	ds_read_b128 v[168:171], v100 offset:6144
	ds_read_b128 v[172:175], v102 offset:6144
	v_exp_f32_e32 v104, v104
	v_exp_f32_e32 v105, v105
	v_exp_f32_e32 v106, v106
	v_add_f32_e32 v144, v104, v105
	v_exp_f32_e32 v107, v107
	v_exp_f32_e32 v108, v108
	v_add_f32_e32 v144, v144, v106
	v_exp_f32_e32 v109, v109
	v_add_f32_e32 v144, v144, v107
	v_exp_f32_e32 v110, v110
	v_add_f32_e32 v144, v144, v108
	v_exp_f32_e32 v111, v111
	v_add_f32_e32 v144, v144, v109
	v_cvt_pk_bf16_f32 v104, v104, v105
	v_add_f32_e32 v144, v144, v110
	v_cvt_pk_bf16_f32 v105, v106, v107
	v_cvt_pk_bf16_f32 v106, v108, v109
	v_cvt_pk_bf16_f32 v107, v110, v111
	v_add_f32_e32 v144, v144, v111
	v_add_f32_e32 v131, v131, v144
	v_exp_f32_e32 v112, v112
	v_exp_f32_e32 v113, v113
	v_exp_f32_e32 v114, v114
	v_add_f32_e32 v144, v112, v113
	v_exp_f32_e32 v115, v115
	v_exp_f32_e32 v116, v116
	v_add_f32_e32 v144, v144, v114
	v_exp_f32_e32 v117, v117
	v_add_f32_e32 v144, v144, v115
	v_exp_f32_e32 v118, v118
	v_add_f32_e32 v144, v144, v116
	v_exp_f32_e32 v119, v119
	v_add_f32_e32 v144, v144, v117
	v_cvt_pk_bf16_f32 v112, v112, v113
	v_add_f32_e32 v144, v144, v118
	v_cvt_pk_bf16_f32 v113, v114, v115
	v_cvt_pk_bf16_f32 v114, v116, v117
	v_cvt_pk_bf16_f32 v115, v118, v119
	v_add_f32_e32 v144, v144, v119
	v_add_f32_e32 v130, v130, v144
	v_exp_f32_e32 v136, v136
	v_exp_f32_e32 v137, v137
	v_exp_f32_e32 v138, v138
	v_add_f32_e32 v144, v136, v137
	v_exp_f32_e32 v139, v139
	v_exp_f32_e32 v140, v140
	v_add_f32_e32 v144, v144, v138
	v_exp_f32_e32 v141, v141
	v_add_f32_e32 v144, v144, v139
	v_exp_f32_e32 v142, v142
	v_add_f32_e32 v144, v144, v140
	v_exp_f32_e32 v143, v143
	v_add_f32_e32 v144, v144, v141
	v_cvt_pk_bf16_f32 v136, v136, v137
	v_add_f32_e32 v144, v144, v142
	v_cvt_pk_bf16_f32 v137, v138, v139
	v_cvt_pk_bf16_f32 v138, v140, v141
	v_cvt_pk_bf16_f32 v139, v142, v143
	v_add_f32_e32 v144, v144, v143
	v_add_f32_e32 v129, v129, v144
	v_exp_f32_e32 v176, v176
	v_exp_f32_e32 v177, v177
	v_exp_f32_e32 v178, v178
	v_add_f32_e32 v144, v176, v177
	v_exp_f32_e32 v179, v179
	v_exp_f32_e32 v232, v232
	v_add_f32_e32 v144, v144, v178
	v_exp_f32_e32 v233, v233
	v_add_f32_e32 v144, v144, v179
	v_exp_f32_e32 v234, v234
	v_add_f32_e32 v144, v144, v232
	v_exp_f32_e32 v235, v235
	v_add_f32_e32 v144, v144, v233
	v_cvt_pk_bf16_f32 v176, v176, v177
	v_add_f32_e32 v144, v144, v234
	v_cvt_pk_bf16_f32 v177, v178, v179
	v_cvt_pk_bf16_f32 v178, v232, v233
	v_cvt_pk_bf16_f32 v179, v234, v235
	v_add_f32_e32 v144, v144, v235
	v_add_f32_e32 v128, v128, v144
	s_waitcnt lgkmcnt(4)
; #define LAS __attribute__((address_space(3)))
; __device__ __forceinline__ s16x4 vtr(const LAS unsigned char* p) { return __builtin_bit_cast(s16x4, __builtin_amdgcn_ds_read_tr16_b64_v4i16((LAS v4i16_t*)p)); }
; __device__ __forceinline__ bf16x8 cat8(s16x4 a, s16x4 b) { return (bf16x8){a[0], a[1], a[2], a[3], b[0], b[1], b[2], b[3]}; }
;     ...
; #pragma unroll
;     for (int gh = 0; gh < 4 / GPB; ++gh) {
;         f32x4 S[GPB][4];
; #pragma unroll
;         for (int kb = 0; kb < 4; ++kb) {
;             const bf16x8 kf0 = *(const LAS bf16x8*)(kb0 + (16 * kb) * 128 + kx0), kf1 = *(const LAS bf16x8*)(kb0 + (16 * kb) * 128 + kx1);
; #pragma unroll
;             for (int gi = 0; gi < GPB; ++gi) { S[gi][kb] = __builtin_amdgcn_mfma_f32_16x16x32_bf16(kf0, qf[GPB * gh + gi][0], cinit, 0, 0, 0);
;                 S[gi][kb] = __builtin_amdgcn_mfma_f32_16x16x32_bf16(kf1, qf[GPB * gh + gi][1], S[gi][kb], 0, 0, 0); } }
;         bf16x8 pf[GPB][2];
; #pragma unroll
;         for (int gi = 0; gi < GPB; ++gi) {
;             if (MASK) {
; #pragma unroll
;                 for (int kb = 0; kb < 4; ++kb)
; #pragma unroll
;                     for (int i = 0; i < 4; ++i) { const int rel = rel0 + 16 * kb + 4 * g + i; S[gi][kb][i] = ((unsigned)(rel + 128) > 256u) ? NEGBIG : S[gi][kb][i]; }
;             }
;             ls[GPB * gh + gi] += exp_step<4>(S[gi]);
;             pf[gi][0] = pack8(S[gi][0], S[gi][1]); pf[gi][1] = pack8(S[gi][2], S[gi][3]);
;         }
; #pragma unroll
;         for (int kc = 0; kc < 2; ++kc)
; #pragma unroll
;             for (int db = 0; db < 4; ++db) {
;                 const LAS unsigned char* va = vrow + ((db ^ swz) << 5) + (32 * kc) * 128;
;                 const bf16x8 vf = cat8(vtr(va), vtr(va + 16 * 128));
; #pragma unroll
;                 for (int gi = 0; gi < GPB; ++gi) O[GPB * gh + gi][db] = __builtin_amdgcn_mfma_f32_16x16x32_bf16(vf, pf[gi][kc], O[GPB * gh + gi][db], 0, 0, 0);
;             }
; __device__ __forceinline__ void swa_phase(LAS unsigned char* lds, const bf16_t* Q, const bf16_t* K, const bf16_t* V, bf16_t* Ob, const float* sink, float negb) {
;     ...
;             if (start + 63 >= tq - 128 && start <= tq + 15 + 128)
;                 full_tile<1, 2, 2>(O, ls, qf, negb, buf, buf + 8192, lane, start - (tq + l15));
	v_mfma_f32_16x16x32_bf16 v[64:67], v[216:219], v[104:107], v[64:67]
	v_mfma_f32_16x16x32_bf16 v[60:63], v[220:223], v[104:107], v[60:63]
	v_mfma_f32_16x16x32_bf16 v[56:59], v[224:227], v[104:107], v[56:59]
	v_mfma_f32_16x16x32_bf16 v[52:55], v[228:231], v[104:107], v[52:55]
	v_mfma_f32_16x16x32_bf16 v[48:51], v[216:219], v[112:115], v[48:51]
	v_mfma_f32_16x16x32_bf16 v[44:47], v[220:223], v[112:115], v[44:47]
	v_mfma_f32_16x16x32_bf16 v[40:43], v[224:227], v[112:115], v[40:43]
	v_mfma_f32_16x16x32_bf16 v[36:39], v[228:231], v[112:115], v[36:39]
	v_mfma_f32_16x16x32_bf16 v[72:75], v[216:219], v[136:139], v[72:75]
	v_mfma_f32_16x16x32_bf16 v[84:87], v[220:223], v[136:139], v[84:87]
	v_mfma_f32_16x16x32_bf16 v[88:91], v[224:227], v[136:139], v[88:91]
	v_mfma_f32_16x16x32_bf16 v[96:99], v[228:231], v[136:139], v[96:99]
	v_mfma_f32_16x16x32_bf16 v[68:71], v[216:219], v[176:179], v[68:71]
	v_mfma_f32_16x16x32_bf16 v[76:79], v[220:223], v[176:179], v[76:79]
	v_mfma_f32_16x16x32_bf16 v[80:83], v[224:227], v[176:179], v[80:83]
	v_mfma_f32_16x16x32_bf16 v[92:95], v[228:231], v[176:179], v[92:95]
	s_waitcnt lgkmcnt(0)
	v_mfma_f32_16x16x32_bf16 v[104:107], v[160:163], v[4:7], v[0:3]
	v_mfma_f32_16x16x32_bf16 v[108:111], v[168:171], v[4:7], v[0:3]
	v_mfma_f32_16x16x32_bf16 v[112:115], v[160:163], v[8:11], v[0:3]
	v_mfma_f32_16x16x32_bf16 v[116:119], v[168:171], v[8:11], v[0:3]
	v_mfma_f32_16x16x32_bf16 v[136:139], v[160:163], v[20:23], v[0:3]
	v_mfma_f32_16x16x32_bf16 v[140:143], v[168:171], v[20:23], v[0:3]
	v_mfma_f32_16x16x32_bf16 v[176:179], v[160:163], v[28:31], v[0:3]
	v_mfma_f32_16x16x32_bf16 v[232:235], v[168:171], v[28:31], v[0:3]
	v_mfma_f32_16x16x32_bf16 v[104:107], v[164:167], v[12:15], v[104:107]
	v_mfma_f32_16x16x32_bf16 v[108:111], v[172:175], v[12:15], v[108:111]
	v_mfma_f32_16x16x32_bf16 v[112:115], v[164:167], v[16:19], v[112:115]
	v_mfma_f32_16x16x32_bf16 v[116:119], v[172:175], v[16:19], v[116:119]
	v_mfma_f32_16x16x32_bf16 v[136:139], v[164:167], v[24:27], v[136:139]
	v_mfma_f32_16x16x32_bf16 v[140:143], v[172:175], v[24:27], v[140:143]
	v_mfma_f32_16x16x32_bf16 v[176:179], v[164:167], v[32:35], v[176:179]
	v_mfma_f32_16x16x32_bf16 v[232:235], v[172:175], v[32:35], v[232:235]
	ds_read_b64_tr_b16 v[216:217], v103 offset:12288
	ds_read_b64_tr_b16 v[218:219], v103 offset:14336
	ds_read_b64_tr_b16 v[220:221], v133 offset:12288
	ds_read_b64_tr_b16 v[222:223], v133 offset:14336
	ds_read_b64_tr_b16 v[224:225], v134 offset:12288
	ds_read_b64_tr_b16 v[226:227], v134 offset:14336
	ds_read_b64_tr_b16 v[228:229], v135 offset:12288
	ds_read_b64_tr_b16 v[230:231], v135 offset:14336
	v_exp_f32_e32 v104, v104
	v_exp_f32_e32 v105, v105
	v_exp_f32_e32 v106, v106
	v_add_f32_e32 v144, v104, v105
	v_exp_f32_e32 v107, v107
	v_exp_f32_e32 v108, v108
	v_add_f32_e32 v144, v144, v106
	v_exp_f32_e32 v109, v109
	v_add_f32_e32 v144, v144, v107
	v_exp_f32_e32 v110, v110
	v_add_f32_e32 v144, v144, v108
	v_exp_f32_e32 v111, v111
	v_add_f32_e32 v144, v144, v109
	v_cvt_pk_bf16_f32 v104, v104, v105
	v_add_f32_e32 v144, v144, v110
	v_cvt_pk_bf16_f32 v105, v106, v107
	v_cvt_pk_bf16_f32 v106, v108, v109
	v_cvt_pk_bf16_f32 v107, v110, v111
	v_add_f32_e32 v144, v144, v111
	v_add_f32_e32 v131, v131, v144
	v_exp_f32_e32 v112, v112
	v_exp_f32_e32 v113, v113
	v_exp_f32_e32 v114, v114
	v_add_f32_e32 v144, v112, v113
	v_exp_f32_e32 v115, v115
	v_exp_f32_e32 v116, v116
	v_add_f32_e32 v144, v144, v114
	v_exp_f32_e32 v117, v117
	v_add_f32_e32 v144, v144, v115
	v_exp_f32_e32 v118, v118
	v_add_f32_e32 v144, v144, v116
	v_exp_f32_e32 v119, v119
	v_add_f32_e32 v144, v144, v117
	v_cvt_pk_bf16_f32 v112, v112, v113
	v_add_f32_e32 v144, v144, v118
	v_cvt_pk_bf16_f32 v113, v114, v115
	v_cvt_pk_bf16_f32 v114, v116, v117
	v_cvt_pk_bf16_f32 v115, v118, v119
	v_add_f32_e32 v144, v144, v119
	v_add_f32_e32 v130, v130, v144
	v_exp_f32_e32 v136, v136
	v_exp_f32_e32 v137, v137
	v_exp_f32_e32 v138, v138
	v_add_f32_e32 v144, v136, v137
	v_exp_f32_e32 v139, v139
	v_exp_f32_e32 v140, v140
	v_add_f32_e32 v144, v144, v138
	v_exp_f32_e32 v141, v141
	v_add_f32_e32 v144, v144, v139
	v_exp_f32_e32 v142, v142
	v_add_f32_e32 v144, v144, v140
	v_exp_f32_e32 v143, v143
	v_add_f32_e32 v144, v144, v141
	v_cvt_pk_bf16_f32 v136, v136, v137
	v_add_f32_e32 v144, v144, v142
	v_cvt_pk_bf16_f32 v137, v138, v139
	v_cvt_pk_bf16_f32 v138, v140, v141
	v_cvt_pk_bf16_f32 v139, v142, v143
	v_add_f32_e32 v144, v144, v143
	v_add_f32_e32 v129, v129, v144
	v_exp_f32_e32 v176, v176
	v_exp_f32_e32 v177, v177
	v_exp_f32_e32 v178, v178
	v_add_f32_e32 v144, v176, v177
	v_exp_f32_e32 v179, v179
	v_exp_f32_e32 v232, v232
	v_add_f32_e32 v144, v144, v178
	v_exp_f32_e32 v233, v233
	v_add_f32_e32 v144, v144, v179
	v_exp_f32_e32 v234, v234
	v_add_f32_e32 v144, v144, v232
	v_exp_f32_e32 v235, v235
	v_add_f32_e32 v144, v144, v233
	v_cvt_pk_bf16_f32 v176, v176, v177
	v_add_f32_e32 v144, v144, v234
	v_cvt_pk_bf16_f32 v177, v178, v179
	v_cvt_pk_bf16_f32 v178, v232, v233
	v_cvt_pk_bf16_f32 v179, v234, v235
	v_add_f32_e32 v144, v144, v235
	v_add_f32_e32 v128, v128, v144
	s_waitcnt lgkmcnt(0)
	v_mfma_f32_16x16x32_bf16 v[64:67], v[216:219], v[104:107], v[64:67]
	v_mfma_f32_16x16x32_bf16 v[60:63], v[220:223], v[104:107], v[60:63]
	v_mfma_f32_16x16x32_bf16 v[56:59], v[224:227], v[104:107], v[56:59]
	v_mfma_f32_16x16x32_bf16 v[52:55], v[228:231], v[104:107], v[52:55]
	v_mfma_f32_16x16x32_bf16 v[48:51], v[216:219], v[112:115], v[48:51]
	v_mfma_f32_16x16x32_bf16 v[44:47], v[220:223], v[112:115], v[44:47]
	v_mfma_f32_16x16x32_bf16 v[40:43], v[224:227], v[112:115], v[40:43]
	v_mfma_f32_16x16x32_bf16 v[36:39], v[228:231], v[112:115], v[36:39]
	v_mfma_f32_16x16x32_bf16 v[72:75], v[216:219], v[136:139], v[72:75]
	v_mfma_f32_16x16x32_bf16 v[84:87], v[220:223], v[136:139], v[84:87]
	v_mfma_f32_16x16x32_bf16 v[88:91], v[224:227], v[136:139], v[88:91]
	v_mfma_f32_16x16x32_bf16 v[96:99], v[228:231], v[136:139], v[96:99]
	v_mfma_f32_16x16x32_bf16 v[68:71], v[216:219], v[176:179], v[68:71]
	v_mfma_f32_16x16x32_bf16 v[76:79], v[220:223], v[176:179], v[76:79]
	v_mfma_f32_16x16x32_bf16 v[80:83], v[224:227], v[176:179], v[80:83]
	v_mfma_f32_16x16x32_bf16 v[92:95], v[228:231], v[176:179], v[92:95]
	s_branch .LBB0_354
